# adds: gpost gains + first two xin sets of ladder 1, and gnext gains of ladder 2, fetched before the row-sum exchange spin (independent of it)
# speedup vs baseline: 1.0044x; 1.0044x over previous
;     __device__ __forceinline__ void exchange(const f32x4 (&acc)[2][2][4][2], const Unit& u, int e, int wr, int wc, int fr, int fq) const {
;     ...
;         if (tid < 256 && lid == 0) __hip_atomic_fetch_add(c, 1u, __ATOMIC_RELAXED, __HIP_MEMORY_SCOPE_AGENT);
;         if (wid == 0) { unsigned sp = 0;
;             while ((unsigned)__builtin_amdgcn_readfirstlane((int)__hip_atomic_load(c, __ATOMIC_RELAXED, __HIP_MEMORY_SCOPE_AGENT)) < 16u) { __builtin_amdgcn_s_sleep(2); if (++sp > (1u << 22)) break; }
;     __device__ __forceinline__ void operator()(f32x4 (&acc)[2][2][4][2], const Unit& u, int wr, int wc, int fr, int fq) const {
;     ...
;             for (int m = 0; m < 4; ++m) { const int rl = ai * 128 + wr * 64 + m * 16 + fr; const float r1 = S[rl]; const size_t off = (size_t)(u.pm * 256 + rl) * DM + col0;
; #pragma unroll
;                 for (int bj = 0; bj < 2; ++bj) { const f32x4 xa = *(const f32x4*)(xin + off + bj * 128), xb = *(const f32x4*)(xin + off + bj * 128 + 4);
;                     const f32x4 ga = *(const f32x4*)(gpost + col0 + bj * 128), gb = *(const f32x4*)(gpost + col0 + bj * 128 + 4);
.LBB0_89:
	s_or_b64 exec, exec, s[50:51]
	s_lshl_b32 s65, s82, 8
	v_add_u32_e32 v164, s65, v170
	v_lshl_or_b32 v162, s78, 8, v190
	v_ashrrev_i32_e32 v165, 31, v164
	v_ashrrev_i32_e32 v163, 31, v162
	v_lshlrev_b64 v[164:165], 12, v[164:165]
	v_lshl_add_u64 v[164:165], s[34:35], 0, v[164:165]
	v_lshlrev_b64 v[158:159], 2, v[162:163]
	v_lshl_add_u64 v[160:161], v[164:165], 0, v[158:159]
	v_lshl_add_u64 v[154:155], s[52:53], 0, v[158:159]
	global_load_dwordx4 v[218:221], v[154:155], off
	global_load_dwordx4 v[222:225], v[154:155], off offset:16
	global_load_dwordx4 v[226:229], v[154:155], off offset:512
	global_load_dwordx4 v[230:233], v[154:155], off offset:528
	global_load_dwordx4 v[202:205], v[160:161], off offset:16
	global_load_dwordx4 v[206:209], v[160:161], off
	global_load_dwordx4 v[210:213], v[160:161], off offset:528
	global_load_dwordx4 v[214:217], v[160:161], off offset:512
	v_add_u32_e32 v164, s65, v173
	v_ashrrev_i32_e32 v165, 31, v164
	v_lshlrev_b64 v[164:165], 12, v[164:165]
	v_lshl_add_u64 v[164:165], s[34:35], 0, v[164:165]
	v_lshl_add_u64 v[162:163], v[164:165], 0, v[158:159]
	global_load_dwordx4 v[234:237], v[162:163], off offset:16
	global_load_dwordx4 v[238:241], v[162:163], off
	global_load_dwordx4 v[242:245], v[162:163], off offset:528
	global_load_dwordx4 v[246:249], v[162:163], off offset:512
	v_readlane_b32 s68, v253, 15
	v_readlane_b32 s69, v253, 16
	s_andn2_b64 vcc, exec, s[68:69]
	s_nop 0
	v_cndmask_b32_e64 v144, 0, 1, s[68:69]
	v_cmp_ne_u32_e64 s[50:51], 1, v144
	s_cbranch_vccnz .LBB0_101
	s_mov_b32 s65, 0x400001
	s_branch .LBB0_92

; #define LAS __attribute__((address_space(3)))
;     __device__ __forceinline__ void operator()(f32x4 (&acc)[2][2][4][2], const Unit& u, int wr, int wc, int fr, int fq) const {
;         const LAS float* S = (const LAS float*)(lds + EN_S);
;         const int col0 = u.pn * 256 + wc * 32 + 8 * fq;
;         exchange(acc, u, 0, wr, wc, fr, fq);
; #pragma unroll
;         for (int ai = 0; ai < 2; ++ai)
; #pragma unroll
;             for (int m = 0; m < 4; ++m) { const int rl = ai * 128 + wr * 64 + m * 16 + fr; const float r1 = S[rl]; const size_t off = (size_t)(u.pm * 256 + rl) * DM + col0;
; #pragma unroll
;                 for (int bj = 0; bj < 2; ++bj) { const f32x4 xa = *(const f32x4*)(xin + off + bj * 128), xb = *(const f32x4*)(xin + off + bj * 128 + 4);
;                     const f32x4 ga = *(const f32x4*)(gpost + col0 + bj * 128), gb = *(const f32x4*)(gpost + col0 + bj * 128 + 4);
;                     const f32x4 v0 = xa + acc[ai][bj][m][0] * r1 * ga, v1 = xb + acc[ai][bj][m][1] * r1 * gb;
;                     *(f32x4*)(xout + off + bj * 128) = v0; *(f32x4*)(xout + off + bj * 128 + 4) = v1; acc[ai][bj][m][0] = v0; acc[ai][bj][m][1] = v1; }
;                 asm volatile("" ::: "memory"); }
.LBB0_103:
	s_or_b64 exec, exec, s[84:85]
	s_lshl_b32 s54, s82, 8
	v_add_u32_e32 v144, s54, v170
	v_lshl_or_b32 v142, s78, 8, v190
	v_ashrrev_i32_e32 v145, 31, v144
	v_ashrrev_i32_e32 v143, 31, v142
	v_lshlrev_b64 v[146:147], 12, v[144:145]
	v_lshl_add_u64 v[146:147], s[34:35], 0, v[146:147]
	v_lshlrev_b64 v[158:159], 2, v[142:143]
	v_lshl_add_u64 v[160:161], v[146:147], 0, v[158:159]
	v_lshl_add_u64 v[154:155], s[52:53], 0, v[158:159]
	s_waitcnt lgkmcnt(0)
	s_barrier
	s_andn2_b64 vcc, exec, s[62:63]
	ds_read_b32 v154, v182
	ds_read_b32 v156, v183
	s_waitcnt lgkmcnt(1)
	v_pk_mul_f32 v[50:51], v[50:51], v[154:155] op_sel_hi:[1,0]
	v_pk_mul_f32 v[52:53], v[52:53], v[154:155] op_sel_hi:[1,0]
	v_pk_mul_f32 v[54:55], v[54:55], v[154:155] op_sel_hi:[1,0]
	v_pk_mul_f32 v[56:57], v[56:57], v[154:155] op_sel_hi:[1,0]
	v_pk_mul_f32 v[62:63], v[62:63], v[154:155] op_sel_hi:[1,0]
	v_pk_mul_f32 v[64:65], v[64:65], v[154:155] op_sel_hi:[1,0]
	v_pk_mul_f32 v[58:59], v[58:59], v[154:155] op_sel_hi:[1,0]
	v_pk_mul_f32 v[60:61], v[60:61], v[154:155] op_sel_hi:[1,0]
	s_waitcnt vmcnt(0)
	v_pk_fma_f32 v[54:55], v[54:55], v[222:223], v[202:203]
	v_pk_fma_f32 v[56:57], v[56:57], v[224:225], v[204:205]
	v_pk_fma_f32 v[50:51], v[50:51], v[218:219], v[206:207]
	v_pk_fma_f32 v[52:53], v[52:53], v[220:221], v[208:209]
	v_pk_fma_f32 v[58:59], v[58:59], v[230:231], v[210:211]
	v_pk_fma_f32 v[60:61], v[60:61], v[232:233], v[212:213]
	v_pk_fma_f32 v[62:63], v[62:63], v[226:227], v[214:215]
	v_pk_fma_f32 v[64:65], v[64:65], v[228:229], v[216:217]
	global_store_dwordx4 v[160:161], v[50:53], off
	global_store_dwordx4 v[160:161], v[54:57], off offset:16
	global_store_dwordx4 v[160:161], v[62:65], off offset:512
	global_store_dwordx4 v[160:161], v[58:61], off offset:528
	v_add_u32_e32 v164, s54, v174
	v_ashrrev_i32_e32 v165, 31, v164
	v_lshlrev_b64 v[164:165], 12, v[164:165]
	v_lshl_add_u64 v[164:165], s[34:35], 0, v[164:165]
	v_lshl_add_u64 v[160:161], v[164:165], 0, v[158:159]
	ds_read_b32 v154, v184
	global_load_dwordx4 v[202:205], v[160:161], off offset:16
	global_load_dwordx4 v[206:209], v[160:161], off
	global_load_dwordx4 v[210:213], v[160:161], off offset:528
	global_load_dwordx4 v[214:217], v[160:161], off offset:512
	s_waitcnt lgkmcnt(1)
	v_pk_mul_f32 v[74:75], v[74:75], v[156:157] op_sel_hi:[1,0]
	v_pk_mul_f32 v[76:77], v[76:77], v[156:157] op_sel_hi:[1,0]
	v_pk_mul_f32 v[78:79], v[78:79], v[156:157] op_sel_hi:[1,0]
	v_pk_mul_f32 v[80:81], v[80:81], v[156:157] op_sel_hi:[1,0]
	v_pk_mul_f32 v[94:95], v[94:95], v[156:157] op_sel_hi:[1,0]
	v_pk_mul_f32 v[96:97], v[96:97], v[156:157] op_sel_hi:[1,0]
	v_pk_mul_f32 v[90:91], v[90:91], v[156:157] op_sel_hi:[1,0]
	v_pk_mul_f32 v[92:93], v[92:93], v[156:157] op_sel_hi:[1,0]
	s_waitcnt vmcnt(8)
	v_pk_fma_f32 v[78:79], v[78:79], v[222:223], v[234:235]
	v_pk_fma_f32 v[80:81], v[80:81], v[224:225], v[236:237]
	v_pk_fma_f32 v[74:75], v[74:75], v[218:219], v[238:239]
	v_pk_fma_f32 v[76:77], v[76:77], v[220:221], v[240:241]
	v_pk_fma_f32 v[90:91], v[90:91], v[230:231], v[242:243]
	v_pk_fma_f32 v[92:93], v[92:93], v[232:233], v[244:245]
	v_pk_fma_f32 v[94:95], v[94:95], v[226:227], v[246:247]
	v_pk_fma_f32 v[96:97], v[96:97], v[228:229], v[248:249]
	global_store_dwordx4 v[162:163], v[74:77], off
	global_store_dwordx4 v[162:163], v[78:81], off offset:16
	global_store_dwordx4 v[162:163], v[94:97], off offset:512
	global_store_dwordx4 v[162:163], v[90:93], off offset:528
	v_add_u32_e32 v164, s54, v175
	v_ashrrev_i32_e32 v165, 31, v164
	v_lshlrev_b64 v[164:165], 12, v[164:165]
	v_lshl_add_u64 v[164:165], s[34:35], 0, v[164:165]
	v_lshl_add_u64 v[162:163], v[164:165], 0, v[158:159]
	ds_read_b32 v156, v185
	global_load_dwordx4 v[234:237], v[162:163], off offset:16
	global_load_dwordx4 v[238:241], v[162:163], off
	global_load_dwordx4 v[242:245], v[162:163], off offset:528
	global_load_dwordx4 v[246:249], v[162:163], off offset:512
	s_waitcnt lgkmcnt(1)
	v_pk_mul_f32 v[98:99], v[98:99], v[154:155] op_sel_hi:[1,0]
	v_pk_mul_f32 v[100:101], v[100:101], v[154:155] op_sel_hi:[1,0]
	v_pk_mul_f32 v[102:103], v[102:103], v[154:155] op_sel_hi:[1,0]
	v_pk_mul_f32 v[104:105], v[104:105], v[154:155] op_sel_hi:[1,0]
	v_pk_mul_f32 v[118:119], v[118:119], v[154:155] op_sel_hi:[1,0]
	v_pk_mul_f32 v[120:121], v[120:121], v[154:155] op_sel_hi:[1,0]
	v_pk_mul_f32 v[114:115], v[114:115], v[154:155] op_sel_hi:[1,0]
	v_pk_mul_f32 v[116:117], v[116:117], v[154:155] op_sel_hi:[1,0]
	s_waitcnt vmcnt(8)
	v_pk_fma_f32 v[102:103], v[102:103], v[222:223], v[202:203]
	v_pk_fma_f32 v[104:105], v[104:105], v[224:225], v[204:205]
	v_pk_fma_f32 v[98:99], v[98:99], v[218:219], v[206:207]
	v_pk_fma_f32 v[100:101], v[100:101], v[220:221], v[208:209]
	v_pk_fma_f32 v[114:115], v[114:115], v[230:231], v[210:211]
	v_pk_fma_f32 v[116:117], v[116:117], v[232:233], v[212:213]
	v_pk_fma_f32 v[118:119], v[118:119], v[226:227], v[214:215]
	v_pk_fma_f32 v[120:121], v[120:121], v[228:229], v[216:217]
	global_store_dwordx4 v[160:161], v[98:101], off
	global_store_dwordx4 v[160:161], v[102:105], off offset:16
	global_store_dwordx4 v[160:161], v[118:121], off offset:512
	global_store_dwordx4 v[160:161], v[114:117], off offset:528
	v_add_u32_e32 v164, s54, v176
	v_ashrrev_i32_e32 v165, 31, v164
	v_lshlrev_b64 v[164:165], 12, v[164:165]
	v_lshl_add_u64 v[164:165], s[34:35], 0, v[164:165]
	v_lshl_add_u64 v[160:161], v[164:165], 0, v[158:159]
	ds_read_b32 v154, v186
	global_load_dwordx4 v[202:205], v[160:161], off offset:16
	global_load_dwordx4 v[206:209], v[160:161], off
	global_load_dwordx4 v[210:213], v[160:161], off offset:528
	global_load_dwordx4 v[214:217], v[160:161], off offset:512
	s_waitcnt lgkmcnt(1)
;     __device__ __forceinline__ void operator()(f32x4 (&acc)[2][2][4][2], const Unit& u, int wr, int wc, int fr, int fq) const {
;     ...
; #pragma unroll
;         for (int ai = 0; ai < 2; ++ai)
; #pragma unroll
;             for (int m = 0; m < 4; ++m) { const int rl = ai * 128 + wr * 64 + m * 16 + fr; const float r1 = S[rl]; const size_t off = (size_t)(u.pm * 256 + rl) * DM + col0;
; #pragma unroll
;                 for (int bj = 0; bj < 2; ++bj) { const f32x4 xa = *(const f32x4*)(xin + off + bj * 128), xb = *(const f32x4*)(xin + off + bj * 128 + 4);
;                     const f32x4 ga = *(const f32x4*)(gpost + col0 + bj * 128), gb = *(const f32x4*)(gpost + col0 + bj * 128 + 4);
;                     const f32x4 v0 = xa + acc[ai][bj][m][0] * r1 * ga, v1 = xb + acc[ai][bj][m][1] * r1 * gb;
;                     *(f32x4*)(xout + off + bj * 128) = v0; *(f32x4*)(xout + off + bj * 128 + 4) = v1; acc[ai][bj][m][0] = v0; acc[ai][bj][m][1] = v1; }
;                 asm volatile("" ::: "memory"); }
	v_pk_mul_f32 v[126:127], v[126:127], v[156:157] op_sel_hi:[1,0]
	v_pk_mul_f32 v[128:129], v[128:129], v[156:157] op_sel_hi:[1,0]
	v_pk_mul_f32 v[122:123], v[122:123], v[156:157] op_sel_hi:[1,0]
	v_pk_mul_f32 v[124:125], v[124:125], v[156:157] op_sel_hi:[1,0]
	v_pk_mul_f32 v[110:111], v[110:111], v[156:157] op_sel_hi:[1,0]
	v_pk_mul_f32 v[112:113], v[112:113], v[156:157] op_sel_hi:[1,0]
	v_pk_mul_f32 v[106:107], v[106:107], v[156:157] op_sel_hi:[1,0]
	v_pk_mul_f32 v[108:109], v[108:109], v[156:157] op_sel_hi:[1,0]
	s_waitcnt vmcnt(8)
	v_pk_fma_f32 v[122:123], v[122:123], v[222:223], v[234:235]
	v_pk_fma_f32 v[124:125], v[124:125], v[224:225], v[236:237]
	v_pk_fma_f32 v[126:127], v[126:127], v[218:219], v[238:239]
	v_pk_fma_f32 v[128:129], v[128:129], v[220:221], v[240:241]
	v_pk_fma_f32 v[106:107], v[106:107], v[230:231], v[242:243]
	v_pk_fma_f32 v[108:109], v[108:109], v[232:233], v[244:245]
	v_pk_fma_f32 v[110:111], v[110:111], v[226:227], v[246:247]
	v_pk_fma_f32 v[112:113], v[112:113], v[228:229], v[248:249]
	global_store_dwordx4 v[162:163], v[126:129], off
	global_store_dwordx4 v[162:163], v[122:125], off offset:16
	global_store_dwordx4 v[162:163], v[110:113], off offset:512
	global_store_dwordx4 v[162:163], v[106:109], off offset:528
	v_add_u32_e32 v164, s54, v177
	v_ashrrev_i32_e32 v165, 31, v164
	v_lshlrev_b64 v[164:165], 12, v[164:165]
	v_lshl_add_u64 v[164:165], s[34:35], 0, v[164:165]
	v_lshl_add_u64 v[162:163], v[164:165], 0, v[158:159]
	ds_read_b32 v156, v187
	global_load_dwordx4 v[234:237], v[162:163], off offset:16
	global_load_dwordx4 v[238:241], v[162:163], off
	global_load_dwordx4 v[242:245], v[162:163], off offset:528
	global_load_dwordx4 v[246:249], v[162:163], off offset:512
	s_waitcnt lgkmcnt(1)
	v_pk_mul_f32 v[86:87], v[86:87], v[154:155] op_sel_hi:[1,0]
	v_pk_mul_f32 v[88:89], v[88:89], v[154:155] op_sel_hi:[1,0]
	v_pk_mul_f32 v[82:83], v[82:83], v[154:155] op_sel_hi:[1,0]
	v_pk_mul_f32 v[84:85], v[84:85], v[154:155] op_sel_hi:[1,0]
	v_pk_mul_f32 v[70:71], v[70:71], v[154:155] op_sel_hi:[1,0]
	v_pk_mul_f32 v[72:73], v[72:73], v[154:155] op_sel_hi:[1,0]
	v_pk_mul_f32 v[66:67], v[66:67], v[154:155] op_sel_hi:[1,0]
	v_pk_mul_f32 v[68:69], v[68:69], v[154:155] op_sel_hi:[1,0]
	s_waitcnt vmcnt(8)
	v_pk_fma_f32 v[82:83], v[82:83], v[222:223], v[202:203]
	v_pk_fma_f32 v[84:85], v[84:85], v[224:225], v[204:205]
	v_pk_fma_f32 v[86:87], v[86:87], v[218:219], v[206:207]
	v_pk_fma_f32 v[88:89], v[88:89], v[220:221], v[208:209]
	v_pk_fma_f32 v[66:67], v[66:67], v[230:231], v[210:211]
	v_pk_fma_f32 v[68:69], v[68:69], v[232:233], v[212:213]
	v_pk_fma_f32 v[70:71], v[70:71], v[226:227], v[214:215]
	v_pk_fma_f32 v[72:73], v[72:73], v[228:229], v[216:217]
	global_store_dwordx4 v[160:161], v[86:89], off
	global_store_dwordx4 v[160:161], v[82:85], off offset:16
	global_store_dwordx4 v[160:161], v[70:73], off offset:512
	global_store_dwordx4 v[160:161], v[66:69], off offset:528
	v_add_u32_e32 v164, s54, v178
	v_ashrrev_i32_e32 v165, 31, v164
	v_lshlrev_b64 v[164:165], 12, v[164:165]
	v_lshl_add_u64 v[164:165], s[34:35], 0, v[164:165]
	v_lshl_add_u64 v[160:161], v[164:165], 0, v[158:159]
	ds_read_b32 v154, v188
	global_load_dwordx4 v[202:205], v[160:161], off offset:16
	global_load_dwordx4 v[206:209], v[160:161], off
	global_load_dwordx4 v[210:213], v[160:161], off offset:528
	global_load_dwordx4 v[214:217], v[160:161], off offset:512
	s_waitcnt lgkmcnt(1)
	v_pk_mul_f32 v[46:47], v[46:47], v[156:157] op_sel_hi:[1,0]
	v_pk_mul_f32 v[48:49], v[48:49], v[156:157] op_sel_hi:[1,0]
	v_pk_mul_f32 v[42:43], v[42:43], v[156:157] op_sel_hi:[1,0]
	v_pk_mul_f32 v[44:45], v[44:45], v[156:157] op_sel_hi:[1,0]
	v_pk_mul_f32 v[38:39], v[38:39], v[156:157] op_sel_hi:[1,0]
	v_pk_mul_f32 v[40:41], v[40:41], v[156:157] op_sel_hi:[1,0]
	v_pk_mul_f32 v[34:35], v[34:35], v[156:157] op_sel_hi:[1,0]
	v_pk_mul_f32 v[36:37], v[36:37], v[156:157] op_sel_hi:[1,0]
	s_waitcnt vmcnt(8)
	v_pk_fma_f32 v[42:43], v[42:43], v[222:223], v[234:235]
	v_pk_fma_f32 v[44:45], v[44:45], v[224:225], v[236:237]
	v_pk_fma_f32 v[46:47], v[46:47], v[218:219], v[238:239]
	v_pk_fma_f32 v[48:49], v[48:49], v[220:221], v[240:241]
	v_pk_fma_f32 v[34:35], v[34:35], v[230:231], v[242:243]
	v_pk_fma_f32 v[36:37], v[36:37], v[232:233], v[244:245]
	v_pk_fma_f32 v[38:39], v[38:39], v[226:227], v[246:247]
	v_pk_fma_f32 v[40:41], v[40:41], v[228:229], v[248:249]
	global_store_dwordx4 v[162:163], v[46:49], off
	global_store_dwordx4 v[162:163], v[42:45], off offset:16
	global_store_dwordx4 v[162:163], v[38:41], off offset:512
	global_store_dwordx4 v[162:163], v[34:37], off offset:528
	v_add_u32_e32 v164, s54, v179
	v_ashrrev_i32_e32 v165, 31, v164
	v_lshlrev_b64 v[164:165], 12, v[164:165]
	v_lshl_add_u64 v[164:165], s[34:35], 0, v[164:165]
	v_lshl_add_u64 v[162:163], v[164:165], 0, v[158:159]
	ds_read_b32 v156, v189
	global_load_dwordx4 v[234:237], v[162:163], off offset:16
	global_load_dwordx4 v[238:241], v[162:163], off
	global_load_dwordx4 v[242:245], v[162:163], off offset:528
	global_load_dwordx4 v[246:249], v[162:163], off offset:512
	s_waitcnt lgkmcnt(1)
	v_pk_mul_f32 v[30:31], v[30:31], v[154:155] op_sel_hi:[1,0]
	v_pk_mul_f32 v[32:33], v[32:33], v[154:155] op_sel_hi:[1,0]
	v_pk_mul_f32 v[26:27], v[26:27], v[154:155] op_sel_hi:[1,0]
	v_pk_mul_f32 v[28:29], v[28:29], v[154:155] op_sel_hi:[1,0]
	v_pk_mul_f32 v[22:23], v[22:23], v[154:155] op_sel_hi:[1,0]
	v_pk_mul_f32 v[24:25], v[24:25], v[154:155] op_sel_hi:[1,0]
	v_pk_mul_f32 v[18:19], v[18:19], v[154:155] op_sel_hi:[1,0]
	v_pk_mul_f32 v[20:21], v[20:21], v[154:155] op_sel_hi:[1,0]
	s_waitcnt vmcnt(8)
; __device__ __forceinline__ float swap_add(float v) { auto rr = __builtin_amdgcn_permlane32_swap(__float_as_uint(v), __float_as_uint(v), false, false); return __uint_as_float(rr[0]) + __uint_as_float(rr[1]); }
;     __device__ __forceinline__ void exchange(const f32x4 (&acc)[2][2][4][2], const Unit& u, int e, int wr, int wc, int fr, int fq) const {
;     ...
; #pragma unroll
;         for (int ai = 0; ai < 2; ++ai)
; #pragma unroll
;             for (int m = 0; m < 4; ++m) { float q = 0.f;
; #pragma unroll
;                 for (int bj = 0; bj < 2; ++bj)
; #pragma unroll
;                     for (int n = 0; n < 2; ++n) { const f32x4 v = acc[ai][bj][m][n]; q += (v[0] * v[0] + v[1] * v[1]) + (v[2] * v[2] + v[3] * v[3]); }
;                 q += __int_as_float(__builtin_amdgcn_ds_bpermute((lid ^ 16) << 2, __float_as_int(q))); q = swap_add(q);
;                 if (fq == 0) P[(ai * 128 + wr * 64 + m * 16 + fr) * 4 + wc] = q; }
;     __device__ __forceinline__ void operator()(f32x4 (&acc)[2][2][4][2], const Unit& u, int wr, int wc, int fr, int fq) const {
;     ...
; #pragma unroll
;         for (int ai = 0; ai < 2; ++ai)
; #pragma unroll
;             for (int m = 0; m < 4; ++m) { const int rl = ai * 128 + wr * 64 + m * 16 + fr; const float r1 = S[rl]; const size_t off = (size_t)(u.pm * 256 + rl) * DM + col0;
; #pragma unroll
;                 for (int bj = 0; bj < 2; ++bj) { const f32x4 xa = *(const f32x4*)(xin + off + bj * 128), xb = *(const f32x4*)(xin + off + bj * 128 + 4);
;                     const f32x4 ga = *(const f32x4*)(gpost + col0 + bj * 128), gb = *(const f32x4*)(gpost + col0 + bj * 128 + 4);
;                     const f32x4 v0 = xa + acc[ai][bj][m][0] * r1 * ga, v1 = xb + acc[ai][bj][m][1] * r1 * gb;
;                     *(f32x4*)(xout + off + bj * 128) = v0; *(f32x4*)(xout + off + bj * 128 + 4) = v1; acc[ai][bj][m][0] = v0; acc[ai][bj][m][1] = v1; }
;                 asm volatile("" ::: "memory"); }
	v_pk_fma_f32 v[26:27], v[26:27], v[222:223], v[202:203]
	v_pk_fma_f32 v[28:29], v[28:29], v[224:225], v[204:205]
	v_pk_fma_f32 v[30:31], v[30:31], v[218:219], v[206:207]
	v_pk_fma_f32 v[32:33], v[32:33], v[220:221], v[208:209]
	v_pk_fma_f32 v[18:19], v[18:19], v[230:231], v[210:211]
	v_pk_fma_f32 v[20:21], v[20:21], v[232:233], v[212:213]
	v_pk_fma_f32 v[22:23], v[22:23], v[226:227], v[214:215]
	v_pk_fma_f32 v[24:25], v[24:25], v[228:229], v[216:217]
	global_store_dwordx4 v[160:161], v[30:33], off
	global_store_dwordx4 v[160:161], v[26:29], off offset:16
	global_store_dwordx4 v[160:161], v[22:25], off offset:512
	global_store_dwordx4 v[160:161], v[18:21], off offset:528
	s_waitcnt lgkmcnt(0)
	v_pk_mul_f32 v[14:15], v[14:15], v[156:157] op_sel_hi:[1,0]
	v_pk_mul_f32 v[16:17], v[16:17], v[156:157] op_sel_hi:[1,0]
	v_pk_mul_f32 v[10:11], v[10:11], v[156:157] op_sel_hi:[1,0]
	v_pk_mul_f32 v[12:13], v[12:13], v[156:157] op_sel_hi:[1,0]
	v_pk_mul_f32 v[6:7], v[6:7], v[156:157] op_sel_hi:[1,0]
	v_pk_mul_f32 v[8:9], v[8:9], v[156:157] op_sel_hi:[1,0]
	v_pk_mul_f32 v[2:3], v[2:3], v[156:157] op_sel_hi:[1,0]
	v_pk_mul_f32 v[4:5], v[4:5], v[156:157] op_sel_hi:[1,0]
	s_waitcnt vmcnt(4)
	v_pk_fma_f32 v[10:11], v[10:11], v[222:223], v[234:235]
	v_pk_fma_f32 v[12:13], v[12:13], v[224:225], v[236:237]
	v_pk_fma_f32 v[14:15], v[14:15], v[218:219], v[238:239]
	v_pk_fma_f32 v[16:17], v[16:17], v[220:221], v[240:241]
	v_pk_fma_f32 v[2:3], v[2:3], v[230:231], v[242:243]
	v_pk_fma_f32 v[4:5], v[4:5], v[232:233], v[244:245]
	v_pk_fma_f32 v[6:7], v[6:7], v[226:227], v[246:247]
	v_pk_fma_f32 v[8:9], v[8:9], v[228:229], v[248:249]
	global_store_dwordx4 v[162:163], v[14:17], off
	global_store_dwordx4 v[162:163], v[10:13], off offset:16
	global_store_dwordx4 v[162:163], v[6:9], off offset:512
	global_store_dwordx4 v[162:163], v[2:5], off offset:528
	v_add_u32_e32 v146, s54, v173
	v_ashrrev_i32_e32 v147, 31, v146
	v_add_u32_e32 v148, s54, v174
	v_ashrrev_i32_e32 v149, 31, v148
	v_add_u32_e32 v150, s54, v175
	v_ashrrev_i32_e32 v151, 31, v150
	v_add_u32_e32 v152, s54, v176
	v_ashrrev_i32_e32 v153, 31, v152
	v_add_u32_e32 v156, s54, v177
	v_ashrrev_i32_e32 v157, 31, v156
	v_add_u32_e32 v166, s54, v178
	v_ashrrev_i32_e32 v167, 31, v166
	v_add_u32_e32 v168, s54, v179
	v_ashrrev_i32_e32 v169, 31, v168
	s_cbranch_vccnz .LBB0_140
	v_mul_f32_e32 v154, v51, v51
	v_mul_f32_e32 v155, v53, v53
	v_fmac_f32_e32 v154, v50, v50
	v_fmac_f32_e32 v155, v52, v52
	v_add_f32_e32 v154, v154, v155
	v_mul_f32_e32 v155, v55, v55
	v_mul_f32_e32 v158, v57, v57
	v_fmac_f32_e32 v155, v54, v54
	v_fmac_f32_e32 v158, v56, v56
	v_add_f32_e32 v155, v155, v158
	v_add_f32_e32 v154, v154, v155
	v_mul_f32_e32 v155, v63, v63
	v_mul_f32_e32 v158, v65, v65
	v_fmac_f32_e32 v155, v62, v62
	v_fmac_f32_e32 v158, v64, v64
	v_add_f32_e32 v155, v155, v158
	v_add_f32_e32 v154, v154, v155
	v_mul_f32_e32 v155, v59, v59
	v_mul_f32_e32 v158, v61, v61
	v_fmac_f32_e32 v155, v58, v58
	v_fmac_f32_e32 v158, v60, v60
	v_add_f32_e32 v155, v155, v158
	v_add_f32_e32 v154, v154, v155
	ds_bpermute_b32 v155, v172, v154
	s_waitcnt lgkmcnt(0)
	v_add_f32_e32 v154, v154, v155
	v_mov_b32_e32 v155, v154
	s_nop 1
	v_permlane32_swap_b32_e32 v154, v155
	s_and_saveexec_b64 s[54:55], s[42:43]
	v_add_f32_e32 v154, v154, v155
	ds_write_b32 v201, v154
	s_or_b64 exec, exec, s[54:55]
	v_mul_f32_e32 v154, v75, v75
	v_mul_f32_e32 v155, v77, v77
	v_fmac_f32_e32 v154, v74, v74
	v_fmac_f32_e32 v155, v76, v76
	v_add_f32_e32 v154, v154, v155
	v_mul_f32_e32 v155, v79, v79
	v_mul_f32_e32 v158, v81, v81
	v_fmac_f32_e32 v155, v78, v78
	v_fmac_f32_e32 v158, v80, v80
	v_add_f32_e32 v155, v155, v158
	v_add_f32_e32 v154, v154, v155
	v_mul_f32_e32 v155, v95, v95
	v_mul_f32_e32 v158, v97, v97
	v_fmac_f32_e32 v155, v94, v94
	v_fmac_f32_e32 v158, v96, v96
	v_add_f32_e32 v155, v155, v158
	v_add_f32_e32 v154, v154, v155
	v_mul_f32_e32 v155, v91, v91
	v_mul_f32_e32 v158, v93, v93
	v_fmac_f32_e32 v155, v90, v90
	v_fmac_f32_e32 v158, v92, v92
	v_add_f32_e32 v155, v155, v158
	v_add_f32_e32 v154, v154, v155
	ds_bpermute_b32 v155, v172, v154
	s_waitcnt lgkmcnt(0)
	v_add_f32_e32 v154, v154, v155
	v_mov_b32_e32 v155, v154
	s_nop 1
	v_permlane32_swap_b32_e32 v154, v155
	s_and_saveexec_b64 s[54:55], s[42:43]
	v_add_f32_e32 v154, v154, v155
	ds_write_b32 v201, v154 offset:256
	s_or_b64 exec, exec, s[54:55]
	v_mul_f32_e32 v154, v99, v99
	v_mul_f32_e32 v155, v101, v101
	v_fmac_f32_e32 v154, v98, v98
	v_fmac_f32_e32 v155, v100, v100
	v_add_f32_e32 v154, v154, v155
	v_mul_f32_e32 v155, v103, v103
	v_mul_f32_e32 v158, v105, v105
	v_fmac_f32_e32 v155, v102, v102
	v_fmac_f32_e32 v158, v104, v104
	v_add_f32_e32 v155, v155, v158
	v_add_f32_e32 v154, v154, v155
	v_mul_f32_e32 v155, v119, v119
	v_mul_f32_e32 v158, v121, v121
	v_fmac_f32_e32 v155, v118, v118
	v_fmac_f32_e32 v158, v120, v120
	v_add_f32_e32 v155, v155, v158
	v_add_f32_e32 v154, v154, v155
	v_mul_f32_e32 v155, v115, v115
	v_mul_f32_e32 v158, v117, v117
	v_fmac_f32_e32 v155, v114, v114
	v_fmac_f32_e32 v158, v116, v116
	v_add_f32_e32 v155, v155, v158
	v_add_f32_e32 v154, v154, v155
	ds_bpermute_b32 v155, v172, v154
	s_waitcnt lgkmcnt(0)
; __device__ __forceinline__ float swap_add(float v) { auto rr = __builtin_amdgcn_permlane32_swap(__float_as_uint(v), __float_as_uint(v), false, false); return __uint_as_float(rr[0]) + __uint_as_float(rr[1]); }
;     __device__ __forceinline__ void exchange(const f32x4 (&acc)[2][2][4][2], const Unit& u, int e, int wr, int wc, int fr, int fq) const {
;     ...
; #pragma unroll
;         for (int ai = 0; ai < 2; ++ai)
; #pragma unroll
;             for (int m = 0; m < 4; ++m) { float q = 0.f;
; #pragma unroll
;                 for (int bj = 0; bj < 2; ++bj)
; #pragma unroll
;                     for (int n = 0; n < 2; ++n) { const f32x4 v = acc[ai][bj][m][n]; q += (v[0] * v[0] + v[1] * v[1]) + (v[2] * v[2] + v[3] * v[3]); }
;                 q += __int_as_float(__builtin_amdgcn_ds_bpermute((lid ^ 16) << 2, __float_as_int(q))); q = swap_add(q);
;                 if (fq == 0) P[(ai * 128 + wr * 64 + m * 16 + fr) * 4 + wc] = q; }
;         __syncthreads();
;         float* xb = xbuf + (size_t)e * T * 4 + (size_t)u.pm * 256 * 4; unsigned* c = cnt + (e * 64 + u.pm) * 64;
;         if (tid < 256) { const float tot = (P[tid * 4] + P[tid * 4 + 1]) + (P[tid * 4 + 2] + P[tid * 4 + 3]);
;             __hip_atomic_store(xb + tid * 4 + u.pn, tot, __ATOMIC_RELAXED, __HIP_MEMORY_SCOPE_AGENT); }
	v_add_f32_e32 v154, v154, v155
	v_mov_b32_e32 v155, v154
	s_nop 1
	v_permlane32_swap_b32_e32 v154, v155
	s_and_saveexec_b64 s[54:55], s[42:43]
	v_add_f32_e32 v154, v154, v155
	ds_write_b32 v201, v154 offset:512
	s_or_b64 exec, exec, s[54:55]
	v_mul_f32_e32 v154, v127, v127
	v_mul_f32_e32 v155, v129, v129
	v_fmac_f32_e32 v154, v126, v126
	v_fmac_f32_e32 v155, v128, v128
	v_add_f32_e32 v154, v154, v155
	v_mul_f32_e32 v155, v123, v123
	v_mul_f32_e32 v158, v125, v125
	v_fmac_f32_e32 v155, v122, v122
	v_fmac_f32_e32 v158, v124, v124
	v_add_f32_e32 v155, v155, v158
	v_add_f32_e32 v154, v154, v155
	v_mul_f32_e32 v155, v111, v111
	v_mul_f32_e32 v158, v113, v113
	v_fmac_f32_e32 v155, v110, v110
	v_fmac_f32_e32 v158, v112, v112
	v_add_f32_e32 v155, v155, v158
	v_add_f32_e32 v154, v154, v155
	v_mul_f32_e32 v155, v107, v107
	v_mul_f32_e32 v158, v109, v109
	v_fmac_f32_e32 v155, v106, v106
	v_fmac_f32_e32 v158, v108, v108
	v_add_f32_e32 v155, v155, v158
	v_add_f32_e32 v154, v154, v155
	ds_bpermute_b32 v155, v172, v154
	s_waitcnt lgkmcnt(0)
	v_add_f32_e32 v154, v154, v155
	v_mov_b32_e32 v155, v154
	s_nop 1
	v_permlane32_swap_b32_e32 v154, v155
	s_and_saveexec_b64 s[54:55], s[42:43]
	v_add_f32_e32 v154, v154, v155
	ds_write_b32 v201, v154 offset:768
	s_or_b64 exec, exec, s[54:55]
	v_mul_f32_e32 v154, v87, v87
	v_mul_f32_e32 v155, v89, v89
	v_fmac_f32_e32 v154, v86, v86
	v_fmac_f32_e32 v155, v88, v88
	v_add_f32_e32 v154, v154, v155
	v_mul_f32_e32 v155, v83, v83
	v_mul_f32_e32 v158, v85, v85
	v_fmac_f32_e32 v155, v82, v82
	v_fmac_f32_e32 v158, v84, v84
	v_add_f32_e32 v155, v155, v158
	v_add_f32_e32 v154, v154, v155
	v_mul_f32_e32 v155, v71, v71
	v_mul_f32_e32 v158, v73, v73
	v_fmac_f32_e32 v155, v70, v70
	v_fmac_f32_e32 v158, v72, v72
	v_add_f32_e32 v155, v155, v158
	v_add_f32_e32 v154, v154, v155
	v_mul_f32_e32 v155, v67, v67
	v_mul_f32_e32 v158, v69, v69
	v_fmac_f32_e32 v155, v66, v66
	v_fmac_f32_e32 v158, v68, v68
	v_add_f32_e32 v155, v155, v158
	v_add_f32_e32 v154, v154, v155
	ds_bpermute_b32 v155, v172, v154
	s_waitcnt lgkmcnt(0)
	v_add_f32_e32 v154, v154, v155
	v_mov_b32_e32 v155, v154
	s_nop 1
	v_permlane32_swap_b32_e32 v154, v155
	s_and_saveexec_b64 s[54:55], s[42:43]
	v_add_f32_e32 v154, v154, v155
	ds_write_b32 v201, v154 offset:2048
	s_or_b64 exec, exec, s[54:55]
	v_mul_f32_e32 v154, v47, v47
	v_mul_f32_e32 v155, v49, v49
	v_fmac_f32_e32 v154, v46, v46
	v_fmac_f32_e32 v155, v48, v48
	v_add_f32_e32 v154, v154, v155
	v_mul_f32_e32 v155, v43, v43
	v_mul_f32_e32 v158, v45, v45
	v_fmac_f32_e32 v155, v42, v42
	v_fmac_f32_e32 v158, v44, v44
	v_add_f32_e32 v155, v155, v158
	v_add_f32_e32 v154, v154, v155
	v_mul_f32_e32 v155, v39, v39
	v_mul_f32_e32 v158, v41, v41
	v_fmac_f32_e32 v155, v38, v38
	v_fmac_f32_e32 v158, v40, v40
	v_add_f32_e32 v155, v155, v158
	v_add_f32_e32 v154, v154, v155
	v_mul_f32_e32 v155, v35, v35
	v_mul_f32_e32 v158, v37, v37
	v_fmac_f32_e32 v155, v34, v34
	v_fmac_f32_e32 v158, v36, v36
	v_add_f32_e32 v155, v155, v158
	v_add_f32_e32 v154, v154, v155
	ds_bpermute_b32 v155, v172, v154
	s_waitcnt lgkmcnt(0)
	v_add_f32_e32 v154, v154, v155
	v_mov_b32_e32 v155, v154
	s_nop 1
	v_permlane32_swap_b32_e32 v154, v155
	s_and_saveexec_b64 s[54:55], s[42:43]
	v_add_f32_e32 v154, v154, v155
	ds_write_b32 v201, v154 offset:2304
	s_or_b64 exec, exec, s[54:55]
	v_mul_f32_e32 v154, v31, v31
	v_mul_f32_e32 v155, v33, v33
	v_fmac_f32_e32 v154, v30, v30
	v_fmac_f32_e32 v155, v32, v32
	v_add_f32_e32 v154, v154, v155
	v_mul_f32_e32 v155, v27, v27
	v_mul_f32_e32 v158, v29, v29
	v_fmac_f32_e32 v155, v26, v26
	v_fmac_f32_e32 v158, v28, v28
	v_add_f32_e32 v155, v155, v158
	v_add_f32_e32 v154, v154, v155
	v_mul_f32_e32 v155, v23, v23
	v_mul_f32_e32 v158, v25, v25
	v_fmac_f32_e32 v155, v22, v22
	v_fmac_f32_e32 v158, v24, v24
	v_add_f32_e32 v155, v155, v158
	v_add_f32_e32 v154, v154, v155
	v_mul_f32_e32 v155, v19, v19
	v_mul_f32_e32 v158, v21, v21
	v_fmac_f32_e32 v155, v18, v18
	v_fmac_f32_e32 v158, v20, v20
	v_add_f32_e32 v155, v155, v158
	v_add_f32_e32 v154, v154, v155
	ds_bpermute_b32 v155, v172, v154
	s_waitcnt lgkmcnt(0)
	v_add_f32_e32 v154, v154, v155
	v_mov_b32_e32 v155, v154
	s_nop 1
	v_permlane32_swap_b32_e32 v154, v155
	s_and_saveexec_b64 s[54:55], s[42:43]
	v_add_f32_e32 v154, v154, v155
	ds_write_b32 v201, v154 offset:2560
	s_or_b64 exec, exec, s[54:55]
	v_mul_f32_e32 v154, v15, v15
	v_mul_f32_e32 v155, v17, v17
	v_fmac_f32_e32 v154, v14, v14
	v_fmac_f32_e32 v155, v16, v16
	v_add_f32_e32 v154, v154, v155
	v_mul_f32_e32 v155, v11, v11
	v_mul_f32_e32 v158, v13, v13
	v_fmac_f32_e32 v155, v10, v10
	v_fmac_f32_e32 v158, v12, v12
	v_add_f32_e32 v155, v155, v158
	v_add_f32_e32 v154, v154, v155
	v_mul_f32_e32 v155, v7, v7
	v_mul_f32_e32 v158, v9, v9
	v_fmac_f32_e32 v155, v6, v6
	v_fmac_f32_e32 v158, v8, v8
	v_add_f32_e32 v155, v155, v158
	v_add_f32_e32 v154, v154, v155
	v_mul_f32_e32 v155, v3, v3
	v_mul_f32_e32 v158, v5, v5
	v_fmac_f32_e32 v155, v2, v2
	v_fmac_f32_e32 v158, v4, v4
	v_add_f32_e32 v155, v155, v158
	v_add_f32_e32 v154, v154, v155
	ds_bpermute_b32 v155, v172, v154
	s_waitcnt lgkmcnt(0)
	v_add_f32_e32 v154, v154, v155
	v_mov_b32_e32 v155, v154
	s_nop 1
	v_permlane32_swap_b32_e32 v154, v155
	s_and_saveexec_b64 s[54:55], s[42:43]
	v_add_f32_e32 v154, v154, v155
	ds_write_b32 v201, v154 offset:2816
	s_or_b64 exec, exec, s[54:55]
	s_add_u32 s12, s92, s12
	s_addc_u32 s13, s94, s13
	v_lshl_add_u64 v[154:155], v[136:137], 2, s[12:13]
	s_waitcnt lgkmcnt(0)
	s_barrier
	s_and_saveexec_b64 s[12:13], s[44:45]
	s_cbranch_execz .LBB0_122
	ds_read_b128 v[202:205], v180
	s_ashr_i32 s79, s78, 31
	v_lshl_add_u64 v[160:161], s[78:79], 2, v[154:155]
	s_waitcnt lgkmcnt(0)
	v_mov_b32_e32 v158, v203
	v_mov_b32_e32 v159, v204
	v_mov_b32_e32 v203, v205
	v_pk_add_f32 v[158:159], v[158:159], v[202:203]
	s_nop 0
	v_pk_add_f32 v[158:159], v[158:159], v[158:159] op_sel:[0,1] op_sel_hi:[1,0]
	global_store_dword v[160:161], v158, off sc1

;     __device__ __forceinline__ void exchange(const f32x4 (&acc)[2][2][4][2], const Unit& u, int e, int wr, int wc, int fr, int fq) const {
;     ...
;         if (tid < 256 && lid == 0) __hip_atomic_fetch_add(c, 1u, __ATOMIC_RELAXED, __HIP_MEMORY_SCOPE_AGENT);
;         if (wid == 0) { unsigned sp = 0;
;             while ((unsigned)__builtin_amdgcn_readfirstlane((int)__hip_atomic_load(c, __ATOMIC_RELAXED, __HIP_MEMORY_SCOPE_AGENT)) < 16u) { __builtin_amdgcn_s_sleep(2); if (++sp > (1u << 22)) break; }
;     __device__ __forceinline__ void operator()(f32x4 (&acc)[2][2][4][2], const Unit& u, int wr, int wc, int fr, int fq) const {
;     ...
;                 for (int m = 0; m < 4; ++m) { const int rl = ai * 128 + wr * 64 + m * 16 + fr; const float r2 = S[rl]; const size_t off = (size_t)(u.pm * 256 + rl) * DM + col0;
; #pragma unroll
;                     for (int bj = 0; bj < 2; ++bj) { const f32x4 ga = *(const f32x4*)(gnext + col0 + bj * 128), gb = *(const f32x4*)(gnext + col0 + bj * 128 + 4);
;                         const f32x4 v0 = acc[ai][bj][m][0] * r2 * ga, v1 = acc[ai][bj][m][1] * r2 * gb;
.LBB0_125:
	s_or_b64 exec, exec, s[54:55]
	v_lshl_add_u64 v[250:251], v[142:143], 2, s[14:15]
	global_load_dwordx4 v[234:237], v[250:251], off
	global_load_dwordx4 v[238:241], v[250:251], off offset:16
	global_load_dwordx4 v[242:245], v[250:251], off offset:512
	global_load_dwordx4 v[246:249], v[250:251], off offset:528
	s_and_b64 vcc, exec, s[50:51]
	s_cbranch_vccnz .LBB0_137
	s_mov_b32 s54, 0x400001
	s_branch .LBB0_128

; __device__ __forceinline__ unsigned cvt_pk_bf16(float lo, float hi) { const f32x2 v = {lo, hi}; const bf16x2_t b = __builtin_convertvector(v, bf16x2_t); return __builtin_bit_cast(unsigned, b); }
;     __device__ __forceinline__ void exchange(const f32x4 (&acc)[2][2][4][2], const Unit& u, int e, int wr, int wc, int fr, int fq) const {
;     ...
;         asm volatile("s_waitcnt vmcnt(0) lgkmcnt(0)" ::: "memory");
;         __syncthreads();
;         if (tid < 256) { float t4 = 0.f;
; #pragma unroll
;             for (int k = 0; k < 4; ++k) t4 += __hip_atomic_load(xb + tid * 4 + k, __ATOMIC_RELAXED, __HIP_MEMORY_SCOPE_AGENT);
;             S[tid] = 1.0f / sqrtf(t4 * (1.f / DM) + EPS); }
;         __syncthreads();
;     __device__ __forceinline__ void operator()(f32x4 (&acc)[2][2][4][2], const Unit& u, int wr, int wc, int fr, int fq) const {
;     ...
; #pragma unroll
;             for (int ai = 0; ai < 2; ++ai)
; #pragma unroll
;                 for (int m = 0; m < 4; ++m) { const int rl = ai * 128 + wr * 64 + m * 16 + fr; const float r2 = S[rl]; const size_t off = (size_t)(u.pm * 256 + rl) * DM + col0;
; #pragma unroll
;                     for (int bj = 0; bj < 2; ++bj) { const f32x4 ga = *(const f32x4*)(gnext + col0 + bj * 128), gb = *(const f32x4*)(gnext + col0 + bj * 128 + 4);
;                         const f32x4 v0 = acc[ai][bj][m][0] * r2 * ga, v1 = acc[ai][bj][m][1] * r2 * gb;
;                         u32x4 w; w.x = cvt_pk_bf16(v0[0], v0[1]); w.y = cvt_pk_bf16(v0[2], v0[3]); w.z = cvt_pk_bf16(v1[0], v1[1]); w.w = cvt_pk_bf16(v1[2], v1[3]);
;                         *(u32x4*)(XN + off + bj * 128) = w; }
;                     asm volatile("" ::: "memory"); }
.LBB0_139:
	s_or_b64 exec, exec, s[12:13]
	s_waitcnt lgkmcnt(0)
	s_waitcnt vmcnt(0)
	s_barrier
	ds_read_b32 v158, v182
	v_lshlrev_b64 v[144:145], 11, v[144:145]
	v_lshlrev_b64 v[142:143], 1, v[142:143]
	v_lshl_add_u64 v[144:145], s[4:5], 0, v[144:145]
	v_lshl_add_u64 v[144:145], v[144:145], 0, v[142:143]
	s_waitcnt lgkmcnt(0)
	v_pk_mul_f32 v[52:53], v[52:53], v[158:159] op_sel_hi:[1,0]
	v_pk_mul_f32 v[50:51], v[50:51], v[158:159] op_sel_hi:[1,0]
	v_pk_mul_f32 v[56:57], v[56:57], v[158:159] op_sel_hi:[1,0]
	v_pk_mul_f32 v[54:55], v[54:55], v[158:159] op_sel_hi:[1,0]
	v_pk_mul_f32 v[64:65], v[64:65], v[158:159] op_sel_hi:[1,0]
	v_pk_mul_f32 v[62:63], v[62:63], v[158:159] op_sel_hi:[1,0]
	v_pk_mul_f32 v[60:61], v[60:61], v[158:159] op_sel_hi:[1,0]
	v_pk_mul_f32 v[58:59], v[58:59], v[158:159] op_sel_hi:[1,0]
	v_pk_mul_f32 v[52:53], v[236:237], v[52:53]
	v_pk_mul_f32 v[50:51], v[234:235], v[50:51]
	v_pk_mul_f32 v[56:57], v[240:241], v[56:57]
	v_pk_mul_f32 v[54:55], v[238:239], v[54:55]
	v_cvt_pk_bf16_f32 v50, v50, v51
	v_cvt_pk_bf16_f32 v51, v52, v53
	v_cvt_pk_bf16_f32 v52, v54, v55
	v_cvt_pk_bf16_f32 v53, v56, v57
	global_store_dwordx4 v[144:145], v[50:53], off
	s_nop 0
	s_nop 0
	v_pk_mul_f32 v[52:53], v[64:65], v[244:245]
	v_pk_mul_f32 v[50:51], v[62:63], v[242:243]
	v_pk_mul_f32 v[56:57], v[60:61], v[248:249]
	v_pk_mul_f32 v[54:55], v[58:59], v[246:247]
	v_cvt_pk_bf16_f32 v50, v50, v51
	v_cvt_pk_bf16_f32 v51, v52, v53
	v_cvt_pk_bf16_f32 v52, v54, v55
	v_cvt_pk_bf16_f32 v53, v56, v57
	global_store_dwordx4 v[144:145], v[50:53], off offset:256
	ds_read_b32 v58, v183
	v_lshlrev_b64 v[60:61], 11, v[146:147]
	v_lshl_add_u64 v[60:61], s[4:5], 0, v[60:61]
	v_lshl_add_u64 v[60:61], v[60:61], 0, v[142:143]
	s_waitcnt lgkmcnt(0)
	v_pk_mul_f32 v[62:63], v[76:77], v[58:59] op_sel_hi:[1,0]
	v_pk_mul_f32 v[64:65], v[74:75], v[58:59] op_sel_hi:[1,0]
	v_pk_mul_f32 v[74:75], v[80:81], v[58:59] op_sel_hi:[1,0]
	v_pk_mul_f32 v[76:77], v[78:79], v[58:59] op_sel_hi:[1,0]
	v_pk_mul_f32 v[52:53], v[236:237], v[62:63]
	v_pk_mul_f32 v[50:51], v[234:235], v[64:65]
	v_pk_mul_f32 v[56:57], v[240:241], v[74:75]
	v_pk_mul_f32 v[54:55], v[238:239], v[76:77]
	v_cvt_pk_bf16_f32 v50, v50, v51
	v_cvt_pk_bf16_f32 v51, v52, v53
	v_cvt_pk_bf16_f32 v52, v54, v55
	v_cvt_pk_bf16_f32 v53, v56, v57
	global_store_dwordx4 v[60:61], v[50:53], off
	s_nop 0
	v_pk_mul_f32 v[62:63], v[96:97], v[58:59] op_sel_hi:[1,0]
	v_pk_mul_f32 v[64:65], v[94:95], v[58:59] op_sel_hi:[1,0]
	v_pk_mul_f32 v[74:75], v[92:93], v[58:59] op_sel_hi:[1,0]
	v_pk_mul_f32 v[58:59], v[90:91], v[58:59] op_sel_hi:[1,0]
	v_pk_mul_f32 v[52:53], v[62:63], v[244:245]
	v_pk_mul_f32 v[50:51], v[64:65], v[242:243]
	v_pk_mul_f32 v[56:57], v[74:75], v[248:249]
	v_pk_mul_f32 v[54:55], v[58:59], v[246:247]
	v_cvt_pk_bf16_f32 v50, v50, v51
	v_cvt_pk_bf16_f32 v51, v52, v53
	v_cvt_pk_bf16_f32 v52, v54, v55
	v_cvt_pk_bf16_f32 v53, v56, v57
	global_store_dwordx4 v[60:61], v[50:53], off offset:256
	ds_read_b32 v58, v184
	v_lshlrev_b64 v[60:61], 11, v[148:149]
	v_lshl_add_u64 v[60:61], s[4:5], 0, v[60:61]
	v_lshl_add_u64 v[60:61], v[60:61], 0, v[142:143]
	s_waitcnt lgkmcnt(0)
	v_pk_mul_f32 v[62:63], v[100:101], v[58:59] op_sel_hi:[1,0]
	v_pk_mul_f32 v[64:65], v[98:99], v[58:59] op_sel_hi:[1,0]
	v_pk_mul_f32 v[74:75], v[104:105], v[58:59] op_sel_hi:[1,0]
	v_pk_mul_f32 v[76:77], v[102:103], v[58:59] op_sel_hi:[1,0]
	v_pk_mul_f32 v[52:53], v[236:237], v[62:63]
	v_pk_mul_f32 v[50:51], v[234:235], v[64:65]
	v_pk_mul_f32 v[56:57], v[240:241], v[74:75]
	v_pk_mul_f32 v[54:55], v[238:239], v[76:77]
	v_cvt_pk_bf16_f32 v50, v50, v51
	v_cvt_pk_bf16_f32 v51, v52, v53
	v_cvt_pk_bf16_f32 v52, v54, v55
	v_cvt_pk_bf16_f32 v53, v56, v57
	global_store_dwordx4 v[60:61], v[50:53], off
	s_nop 0
	v_pk_mul_f32 v[62:63], v[120:121], v[58:59] op_sel_hi:[1,0]
	v_pk_mul_f32 v[64:65], v[118:119], v[58:59] op_sel_hi:[1,0]
	v_pk_mul_f32 v[74:75], v[116:117], v[58:59] op_sel_hi:[1,0]
	v_pk_mul_f32 v[58:59], v[114:115], v[58:59] op_sel_hi:[1,0]
	v_pk_mul_f32 v[52:53], v[62:63], v[244:245]
	v_pk_mul_f32 v[50:51], v[64:65], v[242:243]
	v_pk_mul_f32 v[56:57], v[74:75], v[248:249]
	v_pk_mul_f32 v[54:55], v[58:59], v[246:247]
	v_cvt_pk_bf16_f32 v50, v50, v51
	v_cvt_pk_bf16_f32 v51, v52, v53
	v_cvt_pk_bf16_f32 v52, v54, v55
	v_cvt_pk_bf16_f32 v53, v56, v57
	global_store_dwordx4 v[60:61], v[50:53], off offset:256
	ds_read_b32 v58, v185
	v_lshlrev_b64 v[60:61], 11, v[150:151]
	v_lshl_add_u64 v[60:61], s[4:5], 0, v[60:61]
	v_lshl_add_u64 v[60:61], v[60:61], 0, v[142:143]
	s_waitcnt lgkmcnt(0)
	v_pk_mul_f32 v[62:63], v[128:129], v[58:59] op_sel_hi:[1,0]
	v_pk_mul_f32 v[64:65], v[126:127], v[58:59] op_sel_hi:[1,0]
	v_pk_mul_f32 v[74:75], v[124:125], v[58:59] op_sel_hi:[1,0]
	v_pk_mul_f32 v[76:77], v[122:123], v[58:59] op_sel_hi:[1,0]
	v_pk_mul_f32 v[52:53], v[236:237], v[62:63]
	v_pk_mul_f32 v[50:51], v[234:235], v[64:65]
	v_pk_mul_f32 v[56:57], v[240:241], v[74:75]
	v_pk_mul_f32 v[54:55], v[238:239], v[76:77]
	v_cvt_pk_bf16_f32 v50, v50, v51
	v_cvt_pk_bf16_f32 v51, v52, v53
	v_cvt_pk_bf16_f32 v52, v54, v55
	v_cvt_pk_bf16_f32 v53, v56, v57
	global_store_dwordx4 v[60:61], v[50:53], off
	s_nop 0
	v_pk_mul_f32 v[62:63], v[112:113], v[58:59] op_sel_hi:[1,0]
	v_pk_mul_f32 v[64:65], v[110:111], v[58:59] op_sel_hi:[1,0]
	v_pk_mul_f32 v[74:75], v[108:109], v[58:59] op_sel_hi:[1,0]
	v_pk_mul_f32 v[58:59], v[106:107], v[58:59] op_sel_hi:[1,0]
	v_pk_mul_f32 v[52:53], v[62:63], v[244:245]
	v_pk_mul_f32 v[50:51], v[64:65], v[242:243]
	v_pk_mul_f32 v[56:57], v[74:75], v[248:249]
	v_pk_mul_f32 v[54:55], v[58:59], v[246:247]
	v_cvt_pk_bf16_f32 v50, v50, v51
	v_cvt_pk_bf16_f32 v51, v52, v53
	v_cvt_pk_bf16_f32 v52, v54, v55
	v_cvt_pk_bf16_f32 v53, v56, v57
	global_store_dwordx4 v[60:61], v[50:53], off offset:256
	ds_read_b32 v58, v186
	v_lshlrev_b64 v[60:61], 11, v[152:153]
	v_lshl_add_u64 v[60:61], s[4:5], 0, v[60:61]
	v_lshl_add_u64 v[60:61], v[60:61], 0, v[142:143]
	s_waitcnt lgkmcnt(0)
; __device__ __forceinline__ unsigned cvt_pk_bf16(float lo, float hi) { const f32x2 v = {lo, hi}; const bf16x2_t b = __builtin_convertvector(v, bf16x2_t); return __builtin_bit_cast(unsigned, b); }
;     __device__ __forceinline__ void operator()(f32x4 (&acc)[2][2][4][2], const Unit& u, int wr, int wc, int fr, int fq) const {
;     ...
;                 for (int m = 0; m < 4; ++m) { const int rl = ai * 128 + wr * 64 + m * 16 + fr; const float r2 = S[rl]; const size_t off = (size_t)(u.pm * 256 + rl) * DM + col0;
; #pragma unroll
;                     for (int bj = 0; bj < 2; ++bj) { const f32x4 ga = *(const f32x4*)(gnext + col0 + bj * 128), gb = *(const f32x4*)(gnext + col0 + bj * 128 + 4);
;                         const f32x4 v0 = acc[ai][bj][m][0] * r2 * ga, v1 = acc[ai][bj][m][1] * r2 * gb;
;                         u32x4 w; w.x = cvt_pk_bf16(v0[0], v0[1]); w.y = cvt_pk_bf16(v0[2], v0[3]); w.z = cvt_pk_bf16(v1[0], v1[1]); w.w = cvt_pk_bf16(v1[2], v1[3]);
;                         *(u32x4*)(XN + off + bj * 128) = w; }
;                     asm volatile("" ::: "memory"); }
	v_pk_mul_f32 v[62:63], v[88:89], v[58:59] op_sel_hi:[1,0]
	v_pk_mul_f32 v[64:65], v[86:87], v[58:59] op_sel_hi:[1,0]
	v_pk_mul_f32 v[74:75], v[84:85], v[58:59] op_sel_hi:[1,0]
	v_pk_mul_f32 v[76:77], v[82:83], v[58:59] op_sel_hi:[1,0]
	v_pk_mul_f32 v[68:69], v[68:69], v[58:59] op_sel_hi:[1,0]
	v_pk_mul_f32 v[52:53], v[236:237], v[62:63]
	v_pk_mul_f32 v[50:51], v[234:235], v[64:65]
	v_pk_mul_f32 v[56:57], v[240:241], v[74:75]
	v_pk_mul_f32 v[54:55], v[238:239], v[76:77]
	v_cvt_pk_bf16_f32 v50, v50, v51
	v_cvt_pk_bf16_f32 v51, v52, v53
	v_cvt_pk_bf16_f32 v52, v54, v55
	v_cvt_pk_bf16_f32 v53, v56, v57
	global_store_dwordx4 v[60:61], v[50:53], off
	s_nop 0
	v_pk_mul_f32 v[62:63], v[72:73], v[58:59] op_sel_hi:[1,0]
	v_pk_mul_f32 v[64:65], v[70:71], v[58:59] op_sel_hi:[1,0]
	v_pk_mul_f32 v[58:59], v[66:67], v[58:59] op_sel_hi:[1,0]
	v_pk_mul_f32 v[52:53], v[62:63], v[244:245]
	v_pk_mul_f32 v[50:51], v[64:65], v[242:243]
	v_pk_mul_f32 v[56:57], v[68:69], v[248:249]
	v_pk_mul_f32 v[54:55], v[58:59], v[246:247]
	v_cvt_pk_bf16_f32 v50, v50, v51
	v_cvt_pk_bf16_f32 v51, v52, v53
	v_cvt_pk_bf16_f32 v52, v54, v55
	v_cvt_pk_bf16_f32 v53, v56, v57
	global_store_dwordx4 v[60:61], v[50:53], off offset:256
	ds_read_b32 v58, v187
	v_lshlrev_b64 v[60:61], 11, v[156:157]
	v_lshl_add_u64 v[60:61], s[4:5], 0, v[60:61]
	v_lshl_add_u64 v[60:61], v[60:61], 0, v[142:143]
	s_waitcnt lgkmcnt(0)
	v_pk_mul_f32 v[48:49], v[48:49], v[58:59] op_sel_hi:[1,0]
	v_pk_mul_f32 v[46:47], v[46:47], v[58:59] op_sel_hi:[1,0]
	v_pk_mul_f32 v[44:45], v[44:45], v[58:59] op_sel_hi:[1,0]
	v_pk_mul_f32 v[42:43], v[42:43], v[58:59] op_sel_hi:[1,0]
	v_pk_mul_f32 v[40:41], v[40:41], v[58:59] op_sel_hi:[1,0]
	v_pk_mul_f32 v[38:39], v[38:39], v[58:59] op_sel_hi:[1,0]
	v_pk_mul_f32 v[36:37], v[36:37], v[58:59] op_sel_hi:[1,0]
	v_pk_mul_f32 v[34:35], v[34:35], v[58:59] op_sel_hi:[1,0]
	v_pk_mul_f32 v[48:49], v[236:237], v[48:49]
	v_pk_mul_f32 v[46:47], v[234:235], v[46:47]
	v_pk_mul_f32 v[50:51], v[240:241], v[44:45]
	v_pk_mul_f32 v[44:45], v[238:239], v[42:43]
	v_cvt_pk_bf16_f32 v42, v46, v47
	v_cvt_pk_bf16_f32 v43, v48, v49
	v_cvt_pk_bf16_f32 v44, v44, v45
	v_cvt_pk_bf16_f32 v45, v50, v51
	global_store_dwordx4 v[60:61], v[42:45], off
	s_nop 0
	v_pk_mul_f32 v[40:41], v[40:41], v[244:245]
	v_pk_mul_f32 v[38:39], v[38:39], v[242:243]
	v_pk_mul_f32 v[42:43], v[36:37], v[248:249]
	v_pk_mul_f32 v[36:37], v[34:35], v[246:247]
	v_cvt_pk_bf16_f32 v34, v38, v39
	v_cvt_pk_bf16_f32 v35, v40, v41
	v_cvt_pk_bf16_f32 v36, v36, v37
	v_cvt_pk_bf16_f32 v37, v42, v43
	global_store_dwordx4 v[60:61], v[34:37], off offset:256
	ds_read_b32 v42, v188
	v_lshlrev_b64 v[44:45], 11, v[166:167]
	v_lshl_add_u64 v[44:45], s[4:5], 0, v[44:45]
	v_lshl_add_u64 v[44:45], v[44:45], 0, v[142:143]
	s_waitcnt lgkmcnt(0)
	v_pk_mul_f32 v[32:33], v[32:33], v[42:43] op_sel_hi:[1,0]
	v_pk_mul_f32 v[30:31], v[30:31], v[42:43] op_sel_hi:[1,0]
	v_pk_mul_f32 v[28:29], v[28:29], v[42:43] op_sel_hi:[1,0]
	v_pk_mul_f32 v[26:27], v[26:27], v[42:43] op_sel_hi:[1,0]
	v_pk_mul_f32 v[24:25], v[24:25], v[42:43] op_sel_hi:[1,0]
	v_pk_mul_f32 v[22:23], v[22:23], v[42:43] op_sel_hi:[1,0]
	v_pk_mul_f32 v[20:21], v[20:21], v[42:43] op_sel_hi:[1,0]
	v_pk_mul_f32 v[18:19], v[18:19], v[42:43] op_sel_hi:[1,0]
	v_pk_mul_f32 v[32:33], v[236:237], v[32:33]
	v_pk_mul_f32 v[30:31], v[234:235], v[30:31]
	v_pk_mul_f32 v[34:35], v[240:241], v[28:29]
	v_pk_mul_f32 v[28:29], v[238:239], v[26:27]
	v_cvt_pk_bf16_f32 v26, v30, v31
	v_cvt_pk_bf16_f32 v27, v32, v33
	v_cvt_pk_bf16_f32 v28, v28, v29
	v_cvt_pk_bf16_f32 v29, v34, v35
	global_store_dwordx4 v[44:45], v[26:29], off
	s_nop 0
	v_pk_mul_f32 v[24:25], v[24:25], v[244:245]
	v_pk_mul_f32 v[22:23], v[22:23], v[242:243]
	v_pk_mul_f32 v[26:27], v[20:21], v[248:249]
	v_pk_mul_f32 v[20:21], v[18:19], v[246:247]
	v_cvt_pk_bf16_f32 v18, v22, v23
	v_cvt_pk_bf16_f32 v19, v24, v25
	v_cvt_pk_bf16_f32 v20, v20, v21
	v_cvt_pk_bf16_f32 v21, v26, v27
	global_store_dwordx4 v[44:45], v[18:21], off offset:256
	ds_read_b32 v26, v189
	v_lshlrev_b64 v[28:29], 11, v[168:169]
	v_lshl_add_u64 v[28:29], s[4:5], 0, v[28:29]
	v_lshl_add_u64 v[28:29], v[28:29], 0, v[142:143]
	s_waitcnt lgkmcnt(0)
	v_pk_mul_f32 v[16:17], v[16:17], v[26:27] op_sel_hi:[1,0]
	v_pk_mul_f32 v[14:15], v[14:15], v[26:27] op_sel_hi:[1,0]
	v_pk_mul_f32 v[12:13], v[12:13], v[26:27] op_sel_hi:[1,0]
	v_pk_mul_f32 v[10:11], v[10:11], v[26:27] op_sel_hi:[1,0]
	v_pk_mul_f32 v[8:9], v[8:9], v[26:27] op_sel_hi:[1,0]
	v_pk_mul_f32 v[6:7], v[6:7], v[26:27] op_sel_hi:[1,0]
	v_pk_mul_f32 v[4:5], v[4:5], v[26:27] op_sel_hi:[1,0]
	v_pk_mul_f32 v[2:3], v[2:3], v[26:27] op_sel_hi:[1,0]
	v_pk_mul_f32 v[16:17], v[236:237], v[16:17]
	v_pk_mul_f32 v[14:15], v[234:235], v[14:15]
	v_pk_mul_f32 v[18:19], v[240:241], v[12:13]
	v_pk_mul_f32 v[12:13], v[238:239], v[10:11]
	v_cvt_pk_bf16_f32 v10, v14, v15
	v_cvt_pk_bf16_f32 v11, v16, v17
	v_cvt_pk_bf16_f32 v12, v12, v13
	v_cvt_pk_bf16_f32 v13, v18, v19
	global_store_dwordx4 v[28:29], v[10:13], off
	s_nop 0
	v_pk_mul_f32 v[8:9], v[8:9], v[244:245]
	v_pk_mul_f32 v[6:7], v[6:7], v[242:243]
	v_pk_mul_f32 v[10:11], v[4:5], v[248:249]
	v_pk_mul_f32 v[4:5], v[2:3], v[246:247]
	v_cvt_pk_bf16_f32 v2, v6, v7
	v_cvt_pk_bf16_f32 v3, v8, v9
	v_cvt_pk_bf16_f32 v4, v4, v5
	v_cvt_pk_bf16_f32 v5, v10, v11
	global_store_dwordx4 v[28:29], v[2:5], off offset:256

;     __device__ __forceinline__ void exchange(const f32x4 (&acc)[2][2][4][2], const Unit& u, int e, int wr, int wc, int fr, int fq) const {
;     ...
;         if (tid < 256 && lid == 0) __hip_atomic_fetch_add(c, 1u, __ATOMIC_RELAXED, __HIP_MEMORY_SCOPE_AGENT);
;         if (wid == 0) { unsigned sp = 0;
;             while ((unsigned)__builtin_amdgcn_readfirstlane((int)__hip_atomic_load(c, __ATOMIC_RELAXED, __HIP_MEMORY_SCOPE_AGENT)) < 16u) { __builtin_amdgcn_s_sleep(2); if (++sp > (1u << 22)) break; }
;             __builtin_amdgcn_fence(__ATOMIC_ACQUIRE, "agent");
;             if (lid == 0) FL[0] = 1u; }
;     __device__ __forceinline__ void operator()(f32x4 (&acc)[2][2][4][2], const Unit& u, int wr, int wc, int fr, int fq) const {
;     ...
;             for (int m = 0; m < 4; ++m) { const int rl = ai * 128 + wr * 64 + m * 16 + fr; const float r1 = S[rl]; const size_t off = (size_t)(u.pm * 256 + rl) * DM + col0;
; #pragma unroll
;                 for (int bj = 0; bj < 2; ++bj) { const f32x4 xa = *(const f32x4*)(xin + off + bj * 128), xb = *(const f32x4*)(xin + off + bj * 128 + 4);
;                     const f32x4 ga = *(const f32x4*)(gpost + col0 + bj * 128), gb = *(const f32x4*)(gpost + col0 + bj * 128 + 4);
.LBB0_221:
	s_or_b64 exec, exec, s[50:51]
	s_lshl_b32 s68, s82, 8
	v_add_u32_e32 v250, s68, v169
	v_lshl_or_b32 v148, s76, 8, v189
	v_ashrrev_i32_e32 v251, 31, v250
	v_ashrrev_i32_e32 v149, 31, v148
	v_lshlrev_b64 v[250:251], 10, v[250:251]
	v_lshl_add_u64 v[250:251], v[250:251], 0, v[148:149]
	v_lshlrev_b64 v[162:163], 2, v[250:251]
	v_lshl_add_u64 v[164:165], s[34:35], 0, v[162:163]
	v_lshl_add_u64 v[154:155], v[148:149], 2, s[52:53]
	global_load_dwordx4 v[218:221], v[154:155], off
	global_load_dwordx4 v[222:225], v[154:155], off offset:16
	global_load_dwordx4 v[226:229], v[154:155], off offset:512
	global_load_dwordx4 v[230:233], v[154:155], off offset:528
	global_load_dwordx4 v[202:205], v[164:165], off offset:16
	global_load_dwordx4 v[206:209], v[164:165], off
	global_load_dwordx4 v[210:213], v[164:165], off offset:528
	global_load_dwordx4 v[214:217], v[164:165], off offset:512
	v_add_u32_e32 v250, s68, v172
	v_ashrrev_i32_e32 v251, 31, v250
	v_lshlrev_b64 v[250:251], 10, v[250:251]
	v_lshl_add_u64 v[250:251], v[250:251], 0, v[148:149]
	v_lshlrev_b64 v[250:251], 2, v[250:251]
	v_lshl_add_u64 v[158:159], s[34:35], 0, v[250:251]
	v_lshl_add_u64 v[160:161], s[14:15], 0, v[250:251]
	global_load_dwordx4 v[234:237], v[158:159], off offset:16
	global_load_dwordx4 v[238:241], v[158:159], off
	global_load_dwordx4 v[242:245], v[158:159], off offset:528
	global_load_dwordx4 v[246:249], v[158:159], off offset:512
	v_readlane_b32 s68, v253, 15
	v_readlane_b32 s69, v253, 16
	s_andn2_b64 vcc, exec, s[68:69]
	s_nop 0
	v_cndmask_b32_e64 v144, 0, 1, s[68:69]
	v_cmp_ne_u32_e64 s[50:51], 1, v144
	s_cbranch_vccnz .LBB0_233
	s_mov_b32 s68, 0x400001
	s_branch .LBB0_224

; #define LAS __attribute__((address_space(3)))
;     __device__ __forceinline__ void exchange(const f32x4 (&acc)[2][2][4][2], const Unit& u, int e, int wr, int wc, int fr, int fq) const {
;     ...
;         __syncthreads();
;     }
;     __device__ __forceinline__ void operator()(f32x4 (&acc)[2][2][4][2], const Unit& u, int wr, int wc, int fr, int fq) const {
;         const LAS float* S = (const LAS float*)(lds + EN_S);
;         const int col0 = u.pn * 256 + wc * 32 + 8 * fq;
;         exchange(acc, u, 0, wr, wc, fr, fq);
; #pragma unroll
;         for (int ai = 0; ai < 2; ++ai)
; #pragma unroll
;             for (int m = 0; m < 4; ++m) { const int rl = ai * 128 + wr * 64 + m * 16 + fr; const float r1 = S[rl]; const size_t off = (size_t)(u.pm * 256 + rl) * DM + col0;
; #pragma unroll
;                 for (int bj = 0; bj < 2; ++bj) { const f32x4 xa = *(const f32x4*)(xin + off + bj * 128), xb = *(const f32x4*)(xin + off + bj * 128 + 4);
;                     const f32x4 ga = *(const f32x4*)(gpost + col0 + bj * 128), gb = *(const f32x4*)(gpost + col0 + bj * 128 + 4);
;                     const f32x4 v0 = xa + acc[ai][bj][m][0] * r1 * ga, v1 = xb + acc[ai][bj][m][1] * r1 * gb;
;                     *(f32x4*)(xout + off + bj * 128) = v0; *(f32x4*)(xout + off + bj * 128 + 4) = v1; acc[ai][bj][m][0] = v0; acc[ai][bj][m][1] = v1; }
.LBB0_235:
	s_or_b64 exec, exec, s[84:85]
	s_lshl_b32 s54, s82, 8
	v_add_u32_e32 v144, s54, v169
	v_lshl_or_b32 v142, s76, 8, v189
	v_ashrrev_i32_e32 v145, 31, v144
	v_ashrrev_i32_e32 v143, 31, v142
	v_lshlrev_b64 v[146:147], 10, v[144:145]
	v_lshl_add_u64 v[146:147], v[146:147], 0, v[142:143]
	v_lshlrev_b64 v[162:163], 2, v[146:147]
	v_lshl_add_u64 v[164:165], s[34:35], 0, v[162:163]
	v_lshl_add_u64 v[154:155], v[142:143], 2, s[52:53]
	s_waitcnt lgkmcnt(0)
	s_barrier
	s_andn2_b64 vcc, exec, s[70:71]
	ds_read_b32 v154, v181
	v_lshl_add_u64 v[162:163], s[14:15], 0, v[162:163]
	ds_read_b32 v156, v182
	s_waitcnt lgkmcnt(1)
	v_pk_mul_f32 v[42:43], v[42:43], v[154:155] op_sel_hi:[1,0]
	v_pk_mul_f32 v[44:45], v[44:45], v[154:155] op_sel_hi:[1,0]
	v_pk_mul_f32 v[46:47], v[46:47], v[154:155] op_sel_hi:[1,0]
	v_pk_mul_f32 v[48:49], v[48:49], v[154:155] op_sel_hi:[1,0]
	v_pk_mul_f32 v[62:63], v[62:63], v[154:155] op_sel_hi:[1,0]
	v_pk_mul_f32 v[64:65], v[64:65], v[154:155] op_sel_hi:[1,0]
	v_pk_mul_f32 v[58:59], v[58:59], v[154:155] op_sel_hi:[1,0]
	v_pk_mul_f32 v[60:61], v[60:61], v[154:155] op_sel_hi:[1,0]
	s_waitcnt vmcnt(0)
	v_pk_fma_f32 v[46:47], v[46:47], v[222:223], v[202:203]
	v_pk_fma_f32 v[48:49], v[48:49], v[224:225], v[204:205]
	v_pk_fma_f32 v[42:43], v[42:43], v[218:219], v[206:207]
	v_pk_fma_f32 v[44:45], v[44:45], v[220:221], v[208:209]
	v_pk_fma_f32 v[58:59], v[58:59], v[230:231], v[210:211]
	v_pk_fma_f32 v[60:61], v[60:61], v[232:233], v[212:213]
	v_pk_fma_f32 v[62:63], v[62:63], v[226:227], v[214:215]
	v_pk_fma_f32 v[64:65], v[64:65], v[228:229], v[216:217]
	global_store_dwordx4 v[162:163], v[42:45], off
	global_store_dwordx4 v[162:163], v[46:49], off offset:16
	global_store_dwordx4 v[162:163], v[62:65], off offset:512
	global_store_dwordx4 v[162:163], v[58:61], off offset:528
	v_add_u32_e32 v250, s54, v173
	v_ashrrev_i32_e32 v251, 31, v250
	v_lshlrev_b64 v[250:251], 10, v[250:251]
	v_lshl_add_u64 v[250:251], v[250:251], 0, v[142:143]
	v_lshlrev_b64 v[250:251], 2, v[250:251]
	v_lshl_add_u64 v[164:165], s[34:35], 0, v[250:251]
	v_lshl_add_u64 v[162:163], s[14:15], 0, v[250:251]
	ds_read_b32 v154, v183
	global_load_dwordx4 v[202:205], v[164:165], off offset:16
	global_load_dwordx4 v[206:209], v[164:165], off
	global_load_dwordx4 v[210:213], v[164:165], off offset:528
	global_load_dwordx4 v[214:217], v[164:165], off offset:512
	s_waitcnt lgkmcnt(1)
	v_pk_mul_f32 v[66:67], v[66:67], v[156:157] op_sel_hi:[1,0]
	v_pk_mul_f32 v[68:69], v[68:69], v[156:157] op_sel_hi:[1,0]
	v_pk_mul_f32 v[70:71], v[70:71], v[156:157] op_sel_hi:[1,0]
	v_pk_mul_f32 v[72:73], v[72:73], v[156:157] op_sel_hi:[1,0]
	v_pk_mul_f32 v[86:87], v[86:87], v[156:157] op_sel_hi:[1,0]
	v_pk_mul_f32 v[88:89], v[88:89], v[156:157] op_sel_hi:[1,0]
	v_pk_mul_f32 v[82:83], v[82:83], v[156:157] op_sel_hi:[1,0]
	v_pk_mul_f32 v[84:85], v[84:85], v[156:157] op_sel_hi:[1,0]
	s_waitcnt vmcnt(8)
	v_pk_fma_f32 v[70:71], v[70:71], v[222:223], v[234:235]
	v_pk_fma_f32 v[72:73], v[72:73], v[224:225], v[236:237]
	v_pk_fma_f32 v[66:67], v[66:67], v[218:219], v[238:239]
	v_pk_fma_f32 v[68:69], v[68:69], v[220:221], v[240:241]
	v_pk_fma_f32 v[82:83], v[82:83], v[230:231], v[242:243]
	v_pk_fma_f32 v[84:85], v[84:85], v[232:233], v[244:245]
	v_pk_fma_f32 v[86:87], v[86:87], v[226:227], v[246:247]
	v_pk_fma_f32 v[88:89], v[88:89], v[228:229], v[248:249]
	global_store_dwordx4 v[160:161], v[66:69], off
	global_store_dwordx4 v[160:161], v[70:73], off offset:16
	global_store_dwordx4 v[160:161], v[86:89], off offset:512
	global_store_dwordx4 v[160:161], v[82:85], off offset:528
	v_add_u32_e32 v250, s54, v174
	v_ashrrev_i32_e32 v251, 31, v250
	v_lshlrev_b64 v[250:251], 10, v[250:251]
	v_lshl_add_u64 v[250:251], v[250:251], 0, v[142:143]
	v_lshlrev_b64 v[250:251], 2, v[250:251]
	v_lshl_add_u64 v[158:159], s[34:35], 0, v[250:251]
	v_lshl_add_u64 v[160:161], s[14:15], 0, v[250:251]
	ds_read_b32 v156, v184
	global_load_dwordx4 v[234:237], v[158:159], off offset:16
	global_load_dwordx4 v[238:241], v[158:159], off
	global_load_dwordx4 v[242:245], v[158:159], off offset:528
	global_load_dwordx4 v[246:249], v[158:159], off offset:512
	s_waitcnt lgkmcnt(1)
	v_pk_mul_f32 v[98:99], v[98:99], v[154:155] op_sel_hi:[1,0]
	v_pk_mul_f32 v[100:101], v[100:101], v[154:155] op_sel_hi:[1,0]
	v_pk_mul_f32 v[102:103], v[102:103], v[154:155] op_sel_hi:[1,0]
	v_pk_mul_f32 v[104:105], v[104:105], v[154:155] op_sel_hi:[1,0]
	v_pk_mul_f32 v[110:111], v[110:111], v[154:155] op_sel_hi:[1,0]
	v_pk_mul_f32 v[112:113], v[112:113], v[154:155] op_sel_hi:[1,0]
	v_pk_mul_f32 v[106:107], v[106:107], v[154:155] op_sel_hi:[1,0]
	v_pk_mul_f32 v[108:109], v[108:109], v[154:155] op_sel_hi:[1,0]
	s_waitcnt vmcnt(8)
	v_pk_fma_f32 v[102:103], v[102:103], v[222:223], v[202:203]
	v_pk_fma_f32 v[104:105], v[104:105], v[224:225], v[204:205]
	v_pk_fma_f32 v[98:99], v[98:99], v[218:219], v[206:207]
	v_pk_fma_f32 v[100:101], v[100:101], v[220:221], v[208:209]
	v_pk_fma_f32 v[106:107], v[106:107], v[230:231], v[210:211]
	v_pk_fma_f32 v[108:109], v[108:109], v[232:233], v[212:213]
	v_pk_fma_f32 v[110:111], v[110:111], v[226:227], v[214:215]
	v_pk_fma_f32 v[112:113], v[112:113], v[228:229], v[216:217]
	global_store_dwordx4 v[162:163], v[98:101], off
	global_store_dwordx4 v[162:163], v[102:105], off offset:16
	global_store_dwordx4 v[162:163], v[110:113], off offset:512
	global_store_dwordx4 v[162:163], v[106:109], off offset:528
	v_add_u32_e32 v250, s54, v175
	v_ashrrev_i32_e32 v251, 31, v250
	v_lshlrev_b64 v[250:251], 10, v[250:251]
	v_lshl_add_u64 v[250:251], v[250:251], 0, v[142:143]
	v_lshlrev_b64 v[250:251], 2, v[250:251]
	v_lshl_add_u64 v[164:165], s[34:35], 0, v[250:251]
	v_lshl_add_u64 v[162:163], s[14:15], 0, v[250:251]
	ds_read_b32 v154, v185
	global_load_dwordx4 v[202:205], v[164:165], off offset:16
	global_load_dwordx4 v[206:209], v[164:165], off
	global_load_dwordx4 v[210:213], v[164:165], off offset:528
	global_load_dwordx4 v[214:217], v[164:165], off offset:512
	s_waitcnt lgkmcnt(1)
;     __device__ __forceinline__ void operator()(f32x4 (&acc)[2][2][4][2], const Unit& u, int wr, int wc, int fr, int fq) const {
;     ...
;             for (int m = 0; m < 4; ++m) { const int rl = ai * 128 + wr * 64 + m * 16 + fr; const float r1 = S[rl]; const size_t off = (size_t)(u.pm * 256 + rl) * DM + col0;
; #pragma unroll
;                 for (int bj = 0; bj < 2; ++bj) { const f32x4 xa = *(const f32x4*)(xin + off + bj * 128), xb = *(const f32x4*)(xin + off + bj * 128 + 4);
;                     const f32x4 ga = *(const f32x4*)(gpost + col0 + bj * 128), gb = *(const f32x4*)(gpost + col0 + bj * 128 + 4);
;                     const f32x4 v0 = xa + acc[ai][bj][m][0] * r1 * ga, v1 = xb + acc[ai][bj][m][1] * r1 * gb;
;                     *(f32x4*)(xout + off + bj * 128) = v0; *(f32x4*)(xout + off + bj * 128 + 4) = v1; acc[ai][bj][m][0] = v0; acc[ai][bj][m][1] = v1; }
	v_pk_mul_f32 v[122:123], v[122:123], v[156:157] op_sel_hi:[1,0]
	v_pk_mul_f32 v[124:125], v[124:125], v[156:157] op_sel_hi:[1,0]
	v_pk_mul_f32 v[126:127], v[126:127], v[156:157] op_sel_hi:[1,0]
	v_pk_mul_f32 v[128:129], v[128:129], v[156:157] op_sel_hi:[1,0]
	v_pk_mul_f32 v[118:119], v[118:119], v[156:157] op_sel_hi:[1,0]
	v_pk_mul_f32 v[120:121], v[120:121], v[156:157] op_sel_hi:[1,0]
	v_pk_mul_f32 v[114:115], v[114:115], v[156:157] op_sel_hi:[1,0]
	v_pk_mul_f32 v[116:117], v[116:117], v[156:157] op_sel_hi:[1,0]
	s_waitcnt vmcnt(8)
	v_pk_fma_f32 v[126:127], v[126:127], v[222:223], v[234:235]
	v_pk_fma_f32 v[128:129], v[128:129], v[224:225], v[236:237]
	v_pk_fma_f32 v[122:123], v[122:123], v[218:219], v[238:239]
	v_pk_fma_f32 v[124:125], v[124:125], v[220:221], v[240:241]
	v_pk_fma_f32 v[114:115], v[114:115], v[230:231], v[242:243]
	v_pk_fma_f32 v[116:117], v[116:117], v[232:233], v[244:245]
	v_pk_fma_f32 v[118:119], v[118:119], v[226:227], v[246:247]
	v_pk_fma_f32 v[120:121], v[120:121], v[228:229], v[248:249]
	global_store_dwordx4 v[160:161], v[122:125], off
	global_store_dwordx4 v[160:161], v[126:129], off offset:16
	global_store_dwordx4 v[160:161], v[118:121], off offset:512
	global_store_dwordx4 v[160:161], v[114:117], off offset:528
	v_add_u32_e32 v250, s54, v176
	v_ashrrev_i32_e32 v251, 31, v250
	v_lshlrev_b64 v[250:251], 10, v[250:251]
	v_lshl_add_u64 v[250:251], v[250:251], 0, v[142:143]
	v_lshlrev_b64 v[250:251], 2, v[250:251]
	v_lshl_add_u64 v[158:159], s[34:35], 0, v[250:251]
	v_lshl_add_u64 v[160:161], s[14:15], 0, v[250:251]
	ds_read_b32 v156, v186
	global_load_dwordx4 v[234:237], v[158:159], off offset:16
	global_load_dwordx4 v[238:241], v[158:159], off
	global_load_dwordx4 v[242:245], v[158:159], off offset:528
	global_load_dwordx4 v[246:249], v[158:159], off offset:512
	s_waitcnt lgkmcnt(1)
	v_pk_mul_f32 v[94:95], v[94:95], v[154:155] op_sel_hi:[1,0]
	v_pk_mul_f32 v[96:97], v[96:97], v[154:155] op_sel_hi:[1,0]
	v_pk_mul_f32 v[90:91], v[90:91], v[154:155] op_sel_hi:[1,0]
	v_pk_mul_f32 v[92:93], v[92:93], v[154:155] op_sel_hi:[1,0]
	v_pk_mul_f32 v[78:79], v[78:79], v[154:155] op_sel_hi:[1,0]
	v_pk_mul_f32 v[80:81], v[80:81], v[154:155] op_sel_hi:[1,0]
	v_pk_mul_f32 v[74:75], v[74:75], v[154:155] op_sel_hi:[1,0]
	v_pk_mul_f32 v[76:77], v[76:77], v[154:155] op_sel_hi:[1,0]
	s_waitcnt vmcnt(8)
	v_pk_fma_f32 v[90:91], v[90:91], v[222:223], v[202:203]
	v_pk_fma_f32 v[92:93], v[92:93], v[224:225], v[204:205]
	v_pk_fma_f32 v[94:95], v[94:95], v[218:219], v[206:207]
	v_pk_fma_f32 v[96:97], v[96:97], v[220:221], v[208:209]
	v_pk_fma_f32 v[74:75], v[74:75], v[230:231], v[210:211]
	v_pk_fma_f32 v[76:77], v[76:77], v[232:233], v[212:213]
	v_pk_fma_f32 v[78:79], v[78:79], v[226:227], v[214:215]
	v_pk_fma_f32 v[80:81], v[80:81], v[228:229], v[216:217]
	global_store_dwordx4 v[162:163], v[94:97], off
	global_store_dwordx4 v[162:163], v[90:93], off offset:16
	global_store_dwordx4 v[162:163], v[78:81], off offset:512
	global_store_dwordx4 v[162:163], v[74:77], off offset:528
	v_add_u32_e32 v250, s54, v177
	v_ashrrev_i32_e32 v251, 31, v250
	v_lshlrev_b64 v[250:251], 10, v[250:251]
	v_lshl_add_u64 v[250:251], v[250:251], 0, v[142:143]
	v_lshlrev_b64 v[250:251], 2, v[250:251]
	v_lshl_add_u64 v[164:165], s[34:35], 0, v[250:251]
	v_lshl_add_u64 v[162:163], s[14:15], 0, v[250:251]
	ds_read_b32 v154, v187
	global_load_dwordx4 v[202:205], v[164:165], off offset:16
	global_load_dwordx4 v[206:209], v[164:165], off
	global_load_dwordx4 v[210:213], v[164:165], off offset:528
	global_load_dwordx4 v[214:217], v[164:165], off offset:512
	s_waitcnt lgkmcnt(1)
	v_pk_mul_f32 v[54:55], v[54:55], v[156:157] op_sel_hi:[1,0]
	v_pk_mul_f32 v[56:57], v[56:57], v[156:157] op_sel_hi:[1,0]
	v_pk_mul_f32 v[50:51], v[50:51], v[156:157] op_sel_hi:[1,0]
	v_pk_mul_f32 v[52:53], v[52:53], v[156:157] op_sel_hi:[1,0]
	v_pk_mul_f32 v[38:39], v[38:39], v[156:157] op_sel_hi:[1,0]
	v_pk_mul_f32 v[40:41], v[40:41], v[156:157] op_sel_hi:[1,0]
	v_pk_mul_f32 v[34:35], v[34:35], v[156:157] op_sel_hi:[1,0]
	v_pk_mul_f32 v[36:37], v[36:37], v[156:157] op_sel_hi:[1,0]
	s_waitcnt vmcnt(8)
	v_pk_fma_f32 v[50:51], v[50:51], v[222:223], v[234:235]
	v_pk_fma_f32 v[52:53], v[52:53], v[224:225], v[236:237]
	v_pk_fma_f32 v[54:55], v[54:55], v[218:219], v[238:239]
	v_pk_fma_f32 v[56:57], v[56:57], v[220:221], v[240:241]
	v_pk_fma_f32 v[34:35], v[34:35], v[230:231], v[242:243]
	v_pk_fma_f32 v[36:37], v[36:37], v[232:233], v[244:245]
	v_pk_fma_f32 v[38:39], v[38:39], v[226:227], v[246:247]
	v_pk_fma_f32 v[40:41], v[40:41], v[228:229], v[248:249]
	global_store_dwordx4 v[160:161], v[54:57], off
	global_store_dwordx4 v[160:161], v[50:53], off offset:16
	global_store_dwordx4 v[160:161], v[38:41], off offset:512
	global_store_dwordx4 v[160:161], v[34:37], off offset:528
	v_add_u32_e32 v250, s54, v178
	v_ashrrev_i32_e32 v251, 31, v250
	v_lshlrev_b64 v[250:251], 10, v[250:251]
	v_lshl_add_u64 v[250:251], v[250:251], 0, v[142:143]
	v_lshlrev_b64 v[250:251], 2, v[250:251]
	v_lshl_add_u64 v[158:159], s[34:35], 0, v[250:251]
	v_lshl_add_u64 v[160:161], s[14:15], 0, v[250:251]
	ds_read_b32 v156, v188
	global_load_dwordx4 v[234:237], v[158:159], off offset:16
	global_load_dwordx4 v[238:241], v[158:159], off
	global_load_dwordx4 v[242:245], v[158:159], off offset:528
	global_load_dwordx4 v[246:249], v[158:159], off offset:512
	s_waitcnt lgkmcnt(1)
	v_pk_mul_f32 v[30:31], v[30:31], v[154:155] op_sel_hi:[1,0]
	v_pk_mul_f32 v[32:33], v[32:33], v[154:155] op_sel_hi:[1,0]
	v_pk_mul_f32 v[26:27], v[26:27], v[154:155] op_sel_hi:[1,0]
	v_pk_mul_f32 v[28:29], v[28:29], v[154:155] op_sel_hi:[1,0]
	v_pk_mul_f32 v[22:23], v[22:23], v[154:155] op_sel_hi:[1,0]
	v_pk_mul_f32 v[24:25], v[24:25], v[154:155] op_sel_hi:[1,0]
	v_pk_mul_f32 v[18:19], v[18:19], v[154:155] op_sel_hi:[1,0]
	v_pk_mul_f32 v[20:21], v[20:21], v[154:155] op_sel_hi:[1,0]
	s_waitcnt vmcnt(8)
; __device__ __forceinline__ float swap_add(float v) { auto rr = __builtin_amdgcn_permlane32_swap(__float_as_uint(v), __float_as_uint(v), false, false); return __uint_as_float(rr[0]) + __uint_as_float(rr[1]); }
;     __device__ __forceinline__ void exchange(const f32x4 (&acc)[2][2][4][2], const Unit& u, int e, int wr, int wc, int fr, int fq) const {
;     ...
;         for (int ai = 0; ai < 2; ++ai)
; #pragma unroll
;             for (int m = 0; m < 4; ++m) { float q = 0.f;
; #pragma unroll
;                 for (int bj = 0; bj < 2; ++bj)
; #pragma unroll
;                     for (int n = 0; n < 2; ++n) { const f32x4 v = acc[ai][bj][m][n]; q += (v[0] * v[0] + v[1] * v[1]) + (v[2] * v[2] + v[3] * v[3]); }
;                 q += __int_as_float(__builtin_amdgcn_ds_bpermute((lid ^ 16) << 2, __float_as_int(q))); q = swap_add(q);
;                 if (fq == 0) P[(ai * 128 + wr * 64 + m * 16 + fr) * 4 + wc] = q; }
;     __device__ __forceinline__ void operator()(f32x4 (&acc)[2][2][4][2], const Unit& u, int wr, int wc, int fr, int fq) const {
;     ...
;             for (int m = 0; m < 4; ++m) { const int rl = ai * 128 + wr * 64 + m * 16 + fr; const float r1 = S[rl]; const size_t off = (size_t)(u.pm * 256 + rl) * DM + col0;
; #pragma unroll
;                 for (int bj = 0; bj < 2; ++bj) { const f32x4 xa = *(const f32x4*)(xin + off + bj * 128), xb = *(const f32x4*)(xin + off + bj * 128 + 4);
;                     const f32x4 ga = *(const f32x4*)(gpost + col0 + bj * 128), gb = *(const f32x4*)(gpost + col0 + bj * 128 + 4);
;                     const f32x4 v0 = xa + acc[ai][bj][m][0] * r1 * ga, v1 = xb + acc[ai][bj][m][1] * r1 * gb;
;                     *(f32x4*)(xout + off + bj * 128) = v0; *(f32x4*)(xout + off + bj * 128 + 4) = v1; acc[ai][bj][m][0] = v0; acc[ai][bj][m][1] = v1; }
;                 asm volatile("" ::: "memory"); }
;         if (gnext) {
;             exchange(acc, u, 1, wr, wc, fr, fq);
	v_pk_fma_f32 v[26:27], v[26:27], v[222:223], v[202:203]
	v_pk_fma_f32 v[28:29], v[28:29], v[224:225], v[204:205]
	v_pk_fma_f32 v[30:31], v[30:31], v[218:219], v[206:207]
	v_pk_fma_f32 v[32:33], v[32:33], v[220:221], v[208:209]
	v_pk_fma_f32 v[18:19], v[18:19], v[230:231], v[210:211]
	v_pk_fma_f32 v[20:21], v[20:21], v[232:233], v[212:213]
	v_pk_fma_f32 v[22:23], v[22:23], v[226:227], v[214:215]
	v_pk_fma_f32 v[24:25], v[24:25], v[228:229], v[216:217]
	global_store_dwordx4 v[162:163], v[30:33], off
	global_store_dwordx4 v[162:163], v[26:29], off offset:16
	global_store_dwordx4 v[162:163], v[22:25], off offset:512
	global_store_dwordx4 v[162:163], v[18:21], off offset:528
	s_waitcnt lgkmcnt(0)
	v_pk_mul_f32 v[14:15], v[14:15], v[156:157] op_sel_hi:[1,0]
	v_pk_mul_f32 v[16:17], v[16:17], v[156:157] op_sel_hi:[1,0]
	v_pk_mul_f32 v[10:11], v[10:11], v[156:157] op_sel_hi:[1,0]
	v_pk_mul_f32 v[12:13], v[12:13], v[156:157] op_sel_hi:[1,0]
	v_pk_mul_f32 v[6:7], v[6:7], v[156:157] op_sel_hi:[1,0]
	v_pk_mul_f32 v[8:9], v[8:9], v[156:157] op_sel_hi:[1,0]
	v_pk_mul_f32 v[2:3], v[2:3], v[156:157] op_sel_hi:[1,0]
	v_pk_mul_f32 v[4:5], v[4:5], v[156:157] op_sel_hi:[1,0]
	s_waitcnt vmcnt(4)
	v_pk_fma_f32 v[10:11], v[10:11], v[222:223], v[234:235]
	v_pk_fma_f32 v[12:13], v[12:13], v[224:225], v[236:237]
	v_pk_fma_f32 v[14:15], v[14:15], v[218:219], v[238:239]
	v_pk_fma_f32 v[16:17], v[16:17], v[220:221], v[240:241]
	v_pk_fma_f32 v[2:3], v[2:3], v[230:231], v[242:243]
	v_pk_fma_f32 v[4:5], v[4:5], v[232:233], v[244:245]
	v_pk_fma_f32 v[6:7], v[6:7], v[226:227], v[246:247]
	v_pk_fma_f32 v[8:9], v[8:9], v[228:229], v[248:249]
	global_store_dwordx4 v[160:161], v[14:17], off
	global_store_dwordx4 v[160:161], v[10:13], off offset:16
	global_store_dwordx4 v[160:161], v[6:9], off offset:512
	global_store_dwordx4 v[160:161], v[2:5], off offset:528
	v_add_u32_e32 v146, s54, v172
	v_ashrrev_i32_e32 v147, 31, v146
	v_add_u32_e32 v148, s54, v173
	v_ashrrev_i32_e32 v149, 31, v148
	v_add_u32_e32 v150, s54, v174
	v_ashrrev_i32_e32 v151, 31, v150
	v_add_u32_e32 v152, s54, v175
	v_ashrrev_i32_e32 v153, 31, v152
	v_add_u32_e32 v156, s54, v176
	v_ashrrev_i32_e32 v157, 31, v156
	v_add_u32_e32 v158, s54, v177
	v_ashrrev_i32_e32 v159, 31, v158
	v_add_u32_e32 v166, s54, v178
	v_ashrrev_i32_e32 v167, 31, v166
	s_cbranch_vccnz .LBB0_272
	v_mul_f32_e32 v154, v43, v43
	v_mul_f32_e32 v155, v45, v45
	v_fmac_f32_e32 v154, v42, v42
	v_fmac_f32_e32 v155, v44, v44
	v_add_f32_e32 v154, v154, v155
	v_mul_f32_e32 v155, v47, v47
	v_mul_f32_e32 v160, v49, v49
	v_fmac_f32_e32 v155, v46, v46
	v_fmac_f32_e32 v160, v48, v48
	v_add_f32_e32 v155, v155, v160
	v_add_f32_e32 v154, v154, v155
	v_mul_f32_e32 v155, v63, v63
	v_mul_f32_e32 v160, v65, v65
	v_fmac_f32_e32 v155, v62, v62
	v_fmac_f32_e32 v160, v64, v64
	v_add_f32_e32 v155, v155, v160
	v_add_f32_e32 v154, v154, v155
	v_mul_f32_e32 v155, v59, v59
	v_mul_f32_e32 v160, v61, v61
	v_fmac_f32_e32 v155, v58, v58
	v_fmac_f32_e32 v160, v60, v60
	v_add_f32_e32 v155, v155, v160
	v_add_f32_e32 v154, v154, v155
	ds_bpermute_b32 v155, v171, v154
	s_waitcnt lgkmcnt(0)
	v_add_f32_e32 v154, v154, v155
	v_mov_b32_e32 v155, v154
	s_nop 1
	v_permlane32_swap_b32_e32 v154, v155
	s_and_saveexec_b64 s[54:55], s[42:43]
	v_add_f32_e32 v154, v154, v155
	ds_write_b32 v191, v154
	s_or_b64 exec, exec, s[54:55]
	v_mul_f32_e32 v154, v67, v67
	v_mul_f32_e32 v155, v69, v69
	v_fmac_f32_e32 v154, v66, v66
	v_fmac_f32_e32 v155, v68, v68
	v_add_f32_e32 v154, v154, v155
	v_mul_f32_e32 v155, v71, v71
	v_mul_f32_e32 v160, v73, v73
	v_fmac_f32_e32 v155, v70, v70
	v_fmac_f32_e32 v160, v72, v72
	v_add_f32_e32 v155, v155, v160
	v_add_f32_e32 v154, v154, v155
	v_mul_f32_e32 v155, v87, v87
	v_mul_f32_e32 v160, v89, v89
	v_fmac_f32_e32 v155, v86, v86
	v_fmac_f32_e32 v160, v88, v88
	v_add_f32_e32 v155, v155, v160
	v_add_f32_e32 v154, v154, v155
	v_mul_f32_e32 v155, v83, v83
	v_mul_f32_e32 v160, v85, v85
	v_fmac_f32_e32 v155, v82, v82
	v_fmac_f32_e32 v160, v84, v84
	v_add_f32_e32 v155, v155, v160
	v_add_f32_e32 v154, v154, v155
	ds_bpermute_b32 v155, v171, v154
	s_waitcnt lgkmcnt(0)
	v_add_f32_e32 v154, v154, v155
	v_mov_b32_e32 v155, v154
	s_nop 1
	v_permlane32_swap_b32_e32 v154, v155
	s_and_saveexec_b64 s[54:55], s[42:43]
	v_add_f32_e32 v154, v154, v155
	ds_write_b32 v191, v154 offset:256
	s_or_b64 exec, exec, s[54:55]
	v_mul_f32_e32 v154, v99, v99
	v_mul_f32_e32 v155, v101, v101
	v_fmac_f32_e32 v154, v98, v98
	v_fmac_f32_e32 v155, v100, v100
	v_add_f32_e32 v154, v154, v155
	v_mul_f32_e32 v155, v103, v103
	v_mul_f32_e32 v160, v105, v105
	v_fmac_f32_e32 v155, v102, v102
	v_fmac_f32_e32 v160, v104, v104
	v_add_f32_e32 v155, v155, v160
	v_add_f32_e32 v154, v154, v155
	v_mul_f32_e32 v155, v111, v111
	v_mul_f32_e32 v160, v113, v113
	v_fmac_f32_e32 v155, v110, v110
	v_fmac_f32_e32 v160, v112, v112
	v_add_f32_e32 v155, v155, v160
	v_add_f32_e32 v154, v154, v155
	v_mul_f32_e32 v155, v107, v107
	v_mul_f32_e32 v160, v109, v109
	v_fmac_f32_e32 v155, v106, v106
	v_fmac_f32_e32 v160, v108, v108
	v_add_f32_e32 v155, v155, v160
	v_add_f32_e32 v154, v154, v155
	ds_bpermute_b32 v155, v171, v154
	s_waitcnt lgkmcnt(0)
; __device__ __forceinline__ float swap_add(float v) { auto rr = __builtin_amdgcn_permlane32_swap(__float_as_uint(v), __float_as_uint(v), false, false); return __uint_as_float(rr[0]) + __uint_as_float(rr[1]); }
;     __device__ __forceinline__ void exchange(const f32x4 (&acc)[2][2][4][2], const Unit& u, int e, int wr, int wc, int fr, int fq) const {
;     ...
;         for (int ai = 0; ai < 2; ++ai)
; #pragma unroll
;             for (int m = 0; m < 4; ++m) { float q = 0.f;
; #pragma unroll
;                 for (int bj = 0; bj < 2; ++bj)
; #pragma unroll
;                     for (int n = 0; n < 2; ++n) { const f32x4 v = acc[ai][bj][m][n]; q += (v[0] * v[0] + v[1] * v[1]) + (v[2] * v[2] + v[3] * v[3]); }
;                 q += __int_as_float(__builtin_amdgcn_ds_bpermute((lid ^ 16) << 2, __float_as_int(q))); q = swap_add(q);
;                 if (fq == 0) P[(ai * 128 + wr * 64 + m * 16 + fr) * 4 + wc] = q; }
;         __syncthreads();
;         float* xb = xbuf + (size_t)e * T * 4 + (size_t)u.pm * 256 * 4; unsigned* c = cnt + (e * 64 + u.pm) * 64;
;         if (tid < 256) { const float tot = (P[tid * 4] + P[tid * 4 + 1]) + (P[tid * 4 + 2] + P[tid * 4 + 3]);
;             __hip_atomic_store(xb + tid * 4 + u.pn, tot, __ATOMIC_RELAXED, __HIP_MEMORY_SCOPE_AGENT); }
	v_add_f32_e32 v154, v154, v155
	v_mov_b32_e32 v155, v154
	s_nop 1
	v_permlane32_swap_b32_e32 v154, v155
	s_and_saveexec_b64 s[54:55], s[42:43]
	v_add_f32_e32 v154, v154, v155
	ds_write_b32 v191, v154 offset:512
	s_or_b64 exec, exec, s[54:55]
	v_mul_f32_e32 v154, v123, v123
	v_mul_f32_e32 v155, v125, v125
	v_fmac_f32_e32 v154, v122, v122
	v_fmac_f32_e32 v155, v124, v124
	v_add_f32_e32 v154, v154, v155
	v_mul_f32_e32 v155, v127, v127
	v_mul_f32_e32 v160, v129, v129
	v_fmac_f32_e32 v155, v126, v126
	v_fmac_f32_e32 v160, v128, v128
	v_add_f32_e32 v155, v155, v160
	v_add_f32_e32 v154, v154, v155
	v_mul_f32_e32 v155, v119, v119
	v_mul_f32_e32 v160, v121, v121
	v_fmac_f32_e32 v155, v118, v118
	v_fmac_f32_e32 v160, v120, v120
	v_add_f32_e32 v155, v155, v160
	v_add_f32_e32 v154, v154, v155
	v_mul_f32_e32 v155, v115, v115
	v_mul_f32_e32 v160, v117, v117
	v_fmac_f32_e32 v155, v114, v114
	v_fmac_f32_e32 v160, v116, v116
	v_add_f32_e32 v155, v155, v160
	v_add_f32_e32 v154, v154, v155
	ds_bpermute_b32 v155, v171, v154
	s_waitcnt lgkmcnt(0)
	v_add_f32_e32 v154, v154, v155
	v_mov_b32_e32 v155, v154
	s_nop 1
	v_permlane32_swap_b32_e32 v154, v155
	s_and_saveexec_b64 s[54:55], s[42:43]
	v_add_f32_e32 v154, v154, v155
	ds_write_b32 v191, v154 offset:768
	s_or_b64 exec, exec, s[54:55]
	v_mul_f32_e32 v154, v95, v95
	v_mul_f32_e32 v155, v97, v97
	v_fmac_f32_e32 v154, v94, v94
	v_fmac_f32_e32 v155, v96, v96
	v_add_f32_e32 v154, v154, v155
	v_mul_f32_e32 v155, v91, v91
	v_mul_f32_e32 v160, v93, v93
	v_fmac_f32_e32 v155, v90, v90
	v_fmac_f32_e32 v160, v92, v92
	v_add_f32_e32 v155, v155, v160
	v_add_f32_e32 v154, v154, v155
	v_mul_f32_e32 v155, v79, v79
	v_mul_f32_e32 v160, v81, v81
	v_fmac_f32_e32 v155, v78, v78
	v_fmac_f32_e32 v160, v80, v80
	v_add_f32_e32 v155, v155, v160
	v_add_f32_e32 v154, v154, v155
	v_mul_f32_e32 v155, v75, v75
	v_mul_f32_e32 v160, v77, v77
	v_fmac_f32_e32 v155, v74, v74
	v_fmac_f32_e32 v160, v76, v76
	v_add_f32_e32 v155, v155, v160
	v_add_f32_e32 v154, v154, v155
	ds_bpermute_b32 v155, v171, v154
	s_waitcnt lgkmcnt(0)
	v_add_f32_e32 v154, v154, v155
	v_mov_b32_e32 v155, v154
	s_nop 1
	v_permlane32_swap_b32_e32 v154, v155
	s_and_saveexec_b64 s[54:55], s[42:43]
	v_add_f32_e32 v154, v154, v155
	ds_write_b32 v191, v154 offset:2048
	s_or_b64 exec, exec, s[54:55]
	v_mul_f32_e32 v154, v55, v55
	v_mul_f32_e32 v155, v57, v57
	v_fmac_f32_e32 v154, v54, v54
	v_fmac_f32_e32 v155, v56, v56
	v_add_f32_e32 v154, v154, v155
	v_mul_f32_e32 v155, v51, v51
	v_mul_f32_e32 v160, v53, v53
	v_fmac_f32_e32 v155, v50, v50
	v_fmac_f32_e32 v160, v52, v52
	v_add_f32_e32 v155, v155, v160
	v_add_f32_e32 v154, v154, v155
	v_mul_f32_e32 v155, v39, v39
	v_mul_f32_e32 v160, v41, v41
	v_fmac_f32_e32 v155, v38, v38
	v_fmac_f32_e32 v160, v40, v40
	v_add_f32_e32 v155, v155, v160
	v_add_f32_e32 v154, v154, v155
	v_mul_f32_e32 v155, v35, v35
	v_mul_f32_e32 v160, v37, v37
	v_fmac_f32_e32 v155, v34, v34
	v_fmac_f32_e32 v160, v36, v36
	v_add_f32_e32 v155, v155, v160
	v_add_f32_e32 v154, v154, v155
	ds_bpermute_b32 v155, v171, v154
	s_waitcnt lgkmcnt(0)
	v_add_f32_e32 v154, v154, v155
	v_mov_b32_e32 v155, v154
	s_nop 1
	v_permlane32_swap_b32_e32 v154, v155
	s_and_saveexec_b64 s[54:55], s[42:43]
	v_add_f32_e32 v154, v154, v155
	ds_write_b32 v191, v154 offset:2304
	s_or_b64 exec, exec, s[54:55]
	v_mul_f32_e32 v154, v31, v31
	v_mul_f32_e32 v155, v33, v33
	v_fmac_f32_e32 v154, v30, v30
	v_fmac_f32_e32 v155, v32, v32
	v_add_f32_e32 v154, v154, v155
	v_mul_f32_e32 v155, v27, v27
	v_mul_f32_e32 v160, v29, v29
	v_fmac_f32_e32 v155, v26, v26
	v_fmac_f32_e32 v160, v28, v28
	v_add_f32_e32 v155, v155, v160
	v_add_f32_e32 v154, v154, v155
	v_mul_f32_e32 v155, v23, v23
	v_mul_f32_e32 v160, v25, v25
	v_fmac_f32_e32 v155, v22, v22
	v_fmac_f32_e32 v160, v24, v24
	v_add_f32_e32 v155, v155, v160
	v_add_f32_e32 v154, v154, v155
	v_mul_f32_e32 v155, v19, v19
	v_mul_f32_e32 v160, v21, v21
	v_fmac_f32_e32 v155, v18, v18
	v_fmac_f32_e32 v160, v20, v20
	v_add_f32_e32 v155, v155, v160
	v_add_f32_e32 v154, v154, v155
	ds_bpermute_b32 v155, v171, v154
	s_waitcnt lgkmcnt(0)
	v_add_f32_e32 v154, v154, v155
	v_mov_b32_e32 v155, v154
	s_nop 1
	v_permlane32_swap_b32_e32 v154, v155
	s_and_saveexec_b64 s[54:55], s[42:43]
	v_add_f32_e32 v154, v154, v155
	ds_write_b32 v191, v154 offset:2560
	s_or_b64 exec, exec, s[54:55]
	v_mul_f32_e32 v154, v15, v15
	v_mul_f32_e32 v155, v17, v17
	v_fmac_f32_e32 v154, v14, v14
	v_fmac_f32_e32 v155, v16, v16
	v_add_f32_e32 v154, v154, v155
	v_mul_f32_e32 v155, v11, v11
	v_mul_f32_e32 v160, v13, v13
	v_fmac_f32_e32 v155, v10, v10
	v_fmac_f32_e32 v160, v12, v12
	v_add_f32_e32 v155, v155, v160
	v_add_f32_e32 v154, v154, v155
	v_mul_f32_e32 v155, v7, v7
	v_mul_f32_e32 v160, v9, v9
	v_fmac_f32_e32 v155, v6, v6
	v_fmac_f32_e32 v160, v8, v8
	v_add_f32_e32 v155, v155, v160
	v_add_f32_e32 v154, v154, v155
	v_mul_f32_e32 v155, v3, v3
	v_mul_f32_e32 v160, v5, v5
	v_fmac_f32_e32 v155, v2, v2
	v_fmac_f32_e32 v160, v4, v4
	v_add_f32_e32 v155, v155, v160
	v_add_f32_e32 v154, v154, v155
	ds_bpermute_b32 v155, v171, v154
	s_waitcnt lgkmcnt(0)
	v_add_f32_e32 v154, v154, v155
	v_mov_b32_e32 v155, v154
	s_nop 1
	v_permlane32_swap_b32_e32 v154, v155
	s_and_saveexec_b64 s[54:55], s[42:43]
	v_add_f32_e32 v154, v154, v155
	ds_write_b32 v191, v154 offset:2816
	s_or_b64 exec, exec, s[54:55]
	s_add_u32 s12, s97, s12
	s_addc_u32 s13, s72, s13
	v_lshl_add_u64 v[154:155], v[136:137], 2, s[12:13]
	s_waitcnt lgkmcnt(0)
	s_barrier
	s_and_saveexec_b64 s[12:13], s[44:45]
	s_cbranch_execz .LBB0_254
	ds_read_b128 v[202:205], v179
	s_ashr_i32 s77, s76, 31
	v_lshl_add_u64 v[162:163], s[76:77], 2, v[154:155]
	s_waitcnt lgkmcnt(0)
	v_mov_b32_e32 v160, v203
	v_mov_b32_e32 v161, v204
	v_mov_b32_e32 v203, v205
	v_pk_add_f32 v[160:161], v[160:161], v[202:203]
	s_nop 0
	v_pk_add_f32 v[160:161], v[160:161], v[160:161] op_sel:[0,1] op_sel_hi:[1,0]
	global_store_dword v[162:163], v160, off sc1

;     __device__ __forceinline__ void exchange(const f32x4 (&acc)[2][2][4][2], const Unit& u, int e, int wr, int wc, int fr, int fq) const {
;     ...
;         if (tid < 256 && lid == 0) __hip_atomic_fetch_add(c, 1u, __ATOMIC_RELAXED, __HIP_MEMORY_SCOPE_AGENT);
;         if (wid == 0) { unsigned sp = 0;
;             while ((unsigned)__builtin_amdgcn_readfirstlane((int)__hip_atomic_load(c, __ATOMIC_RELAXED, __HIP_MEMORY_SCOPE_AGENT)) < 16u) { __builtin_amdgcn_s_sleep(2); if (++sp > (1u << 22)) break; }
;             __builtin_amdgcn_fence(__ATOMIC_ACQUIRE, "agent");
;             if (lid == 0) FL[0] = 1u; }
;     __device__ __forceinline__ void operator()(f32x4 (&acc)[2][2][4][2], const Unit& u, int wr, int wc, int fr, int fq) const {
;     ...
;                     for (int bj = 0; bj < 2; ++bj) { const f32x4 ga = *(const f32x4*)(gnext + col0 + bj * 128), gb = *(const f32x4*)(gnext + col0 + bj * 128 + 4);
.LBB0_257:
	s_or_b64 exec, exec, s[54:55]
	v_lshl_add_u64 v[250:251], v[142:143], 2, s[62:63]
	global_load_dwordx4 v[234:237], v[250:251], off
	global_load_dwordx4 v[238:241], v[250:251], off offset:16
	global_load_dwordx4 v[242:245], v[250:251], off offset:512
	global_load_dwordx4 v[246:249], v[250:251], off offset:528
	s_and_b64 vcc, exec, s[50:51]
	s_cbranch_vccnz .LBB0_269
	s_mov_b32 s54, 0x400001
	s_branch .LBB0_260

; __device__ __forceinline__ unsigned cvt_pk_bf16(float lo, float hi) { const f32x2 v = {lo, hi}; const bf16x2_t b = __builtin_convertvector(v, bf16x2_t); return __builtin_bit_cast(unsigned, b); }
;     __device__ __forceinline__ void operator()(f32x4 (&acc)[2][2][4][2], const Unit& u, int wr, int wc, int fr, int fq) const {
;     ...
;                 for (int m = 0; m < 4; ++m) { const int rl = ai * 128 + wr * 64 + m * 16 + fr; const float r2 = S[rl]; const size_t off = (size_t)(u.pm * 256 + rl) * DM + col0;
; #pragma unroll
;                     for (int bj = 0; bj < 2; ++bj) { const f32x4 ga = *(const f32x4*)(gnext + col0 + bj * 128), gb = *(const f32x4*)(gnext + col0 + bj * 128 + 4);
;                         const f32x4 v0 = acc[ai][bj][m][0] * r2 * ga, v1 = acc[ai][bj][m][1] * r2 * gb;
;                         u32x4 w; w.x = cvt_pk_bf16(v0[0], v0[1]); w.y = cvt_pk_bf16(v0[2], v0[3]); w.z = cvt_pk_bf16(v1[0], v1[1]); w.w = cvt_pk_bf16(v1[2], v1[3]);
;                         *(u32x4*)(XN + off + bj * 128) = w; }
;                     asm volatile("" ::: "memory"); }
.LBB0_271:
	s_or_b64 exec, exec, s[12:13]
	s_waitcnt lgkmcnt(0)
	s_barrier
	s_waitcnt vmcnt(0)
	ds_read_b32 v160, v181
	v_lshlrev_b64 v[144:145], 11, v[144:145]
	v_lshlrev_b64 v[142:143], 1, v[142:143]
	v_lshl_add_u64 v[144:145], s[4:5], 0, v[144:145]
	v_lshl_add_u64 v[144:145], v[144:145], 0, v[142:143]
	s_waitcnt lgkmcnt(0)
	v_pk_mul_f32 v[44:45], v[44:45], v[160:161] op_sel_hi:[1,0]
	v_pk_mul_f32 v[42:43], v[42:43], v[160:161] op_sel_hi:[1,0]
	v_pk_mul_f32 v[48:49], v[48:49], v[160:161] op_sel_hi:[1,0]
	v_pk_mul_f32 v[46:47], v[46:47], v[160:161] op_sel_hi:[1,0]
	v_pk_mul_f32 v[64:65], v[64:65], v[160:161] op_sel_hi:[1,0]
	v_pk_mul_f32 v[62:63], v[62:63], v[160:161] op_sel_hi:[1,0]
	v_pk_mul_f32 v[60:61], v[60:61], v[160:161] op_sel_hi:[1,0]
	v_pk_mul_f32 v[58:59], v[58:59], v[160:161] op_sel_hi:[1,0]
	v_pk_mul_f32 v[44:45], v[236:237], v[44:45]
	v_pk_mul_f32 v[42:43], v[234:235], v[42:43]
	v_pk_mul_f32 v[48:49], v[240:241], v[48:49]
	v_pk_mul_f32 v[46:47], v[238:239], v[46:47]
	v_cvt_pk_bf16_f32 v42, v42, v43
	v_cvt_pk_bf16_f32 v43, v44, v45
	v_cvt_pk_bf16_f32 v44, v46, v47
	v_cvt_pk_bf16_f32 v45, v48, v49
	global_store_dwordx4 v[144:145], v[42:45], off
	s_nop 0
	s_nop 0
	v_pk_mul_f32 v[44:45], v[64:65], v[244:245]
	v_pk_mul_f32 v[42:43], v[62:63], v[242:243]
	v_pk_mul_f32 v[48:49], v[60:61], v[248:249]
	v_pk_mul_f32 v[46:47], v[58:59], v[246:247]
	v_cvt_pk_bf16_f32 v42, v42, v43
	v_cvt_pk_bf16_f32 v43, v44, v45
	v_cvt_pk_bf16_f32 v44, v46, v47
	v_cvt_pk_bf16_f32 v45, v48, v49
	global_store_dwordx4 v[144:145], v[42:45], off offset:256
	ds_read_b32 v58, v182
	v_lshlrev_b64 v[60:61], 11, v[146:147]
	v_lshl_add_u64 v[60:61], s[4:5], 0, v[60:61]
	v_lshl_add_u64 v[60:61], v[60:61], 0, v[142:143]
	s_waitcnt lgkmcnt(0)
	v_pk_mul_f32 v[62:63], v[68:69], v[58:59] op_sel_hi:[1,0]
	v_pk_mul_f32 v[64:65], v[66:67], v[58:59] op_sel_hi:[1,0]
	v_pk_mul_f32 v[66:67], v[72:73], v[58:59] op_sel_hi:[1,0]
	v_pk_mul_f32 v[68:69], v[70:71], v[58:59] op_sel_hi:[1,0]
	v_pk_mul_f32 v[44:45], v[236:237], v[62:63]
	v_pk_mul_f32 v[42:43], v[234:235], v[64:65]
	v_pk_mul_f32 v[48:49], v[240:241], v[66:67]
	v_pk_mul_f32 v[46:47], v[238:239], v[68:69]
	v_cvt_pk_bf16_f32 v42, v42, v43
	v_cvt_pk_bf16_f32 v43, v44, v45
	v_cvt_pk_bf16_f32 v44, v46, v47
	v_cvt_pk_bf16_f32 v45, v48, v49
	global_store_dwordx4 v[60:61], v[42:45], off
	s_nop 0
	v_pk_mul_f32 v[62:63], v[88:89], v[58:59] op_sel_hi:[1,0]
	v_pk_mul_f32 v[64:65], v[86:87], v[58:59] op_sel_hi:[1,0]
	v_pk_mul_f32 v[66:67], v[84:85], v[58:59] op_sel_hi:[1,0]
	v_pk_mul_f32 v[58:59], v[82:83], v[58:59] op_sel_hi:[1,0]
	v_pk_mul_f32 v[44:45], v[62:63], v[244:245]
	v_pk_mul_f32 v[42:43], v[64:65], v[242:243]
	v_pk_mul_f32 v[48:49], v[66:67], v[248:249]
	v_pk_mul_f32 v[46:47], v[58:59], v[246:247]
	v_cvt_pk_bf16_f32 v42, v42, v43
	v_cvt_pk_bf16_f32 v43, v44, v45
	v_cvt_pk_bf16_f32 v44, v46, v47
	v_cvt_pk_bf16_f32 v45, v48, v49
	global_store_dwordx4 v[60:61], v[42:45], off offset:256
	ds_read_b32 v58, v183
	v_lshlrev_b64 v[60:61], 11, v[148:149]
	v_lshl_add_u64 v[60:61], s[4:5], 0, v[60:61]
	v_lshl_add_u64 v[60:61], v[60:61], 0, v[142:143]
	s_waitcnt lgkmcnt(0)
	v_pk_mul_f32 v[62:63], v[100:101], v[58:59] op_sel_hi:[1,0]
	v_pk_mul_f32 v[64:65], v[98:99], v[58:59] op_sel_hi:[1,0]
	v_pk_mul_f32 v[66:67], v[104:105], v[58:59] op_sel_hi:[1,0]
	v_pk_mul_f32 v[68:69], v[102:103], v[58:59] op_sel_hi:[1,0]
	v_pk_mul_f32 v[44:45], v[236:237], v[62:63]
	v_pk_mul_f32 v[42:43], v[234:235], v[64:65]
	v_pk_mul_f32 v[48:49], v[240:241], v[66:67]
	v_pk_mul_f32 v[46:47], v[238:239], v[68:69]
	v_cvt_pk_bf16_f32 v42, v42, v43
	v_cvt_pk_bf16_f32 v43, v44, v45
	v_cvt_pk_bf16_f32 v44, v46, v47
	v_cvt_pk_bf16_f32 v45, v48, v49
	global_store_dwordx4 v[60:61], v[42:45], off
	s_nop 0
	v_pk_mul_f32 v[62:63], v[112:113], v[58:59] op_sel_hi:[1,0]
	v_pk_mul_f32 v[64:65], v[110:111], v[58:59] op_sel_hi:[1,0]
	v_pk_mul_f32 v[66:67], v[108:109], v[58:59] op_sel_hi:[1,0]
	v_pk_mul_f32 v[58:59], v[106:107], v[58:59] op_sel_hi:[1,0]
	v_pk_mul_f32 v[44:45], v[62:63], v[244:245]
	v_pk_mul_f32 v[42:43], v[64:65], v[242:243]
	v_pk_mul_f32 v[48:49], v[66:67], v[248:249]
	v_pk_mul_f32 v[46:47], v[58:59], v[246:247]
	v_cvt_pk_bf16_f32 v42, v42, v43
	v_cvt_pk_bf16_f32 v43, v44, v45
	v_cvt_pk_bf16_f32 v44, v46, v47
	v_cvt_pk_bf16_f32 v45, v48, v49
	global_store_dwordx4 v[60:61], v[42:45], off offset:256
	ds_read_b32 v58, v184
	v_lshlrev_b64 v[60:61], 11, v[150:151]
	v_lshl_add_u64 v[60:61], s[4:5], 0, v[60:61]
	v_lshl_add_u64 v[60:61], v[60:61], 0, v[142:143]
	s_waitcnt lgkmcnt(0)
	v_pk_mul_f32 v[62:63], v[124:125], v[58:59] op_sel_hi:[1,0]
	v_pk_mul_f32 v[64:65], v[122:123], v[58:59] op_sel_hi:[1,0]
	v_pk_mul_f32 v[66:67], v[128:129], v[58:59] op_sel_hi:[1,0]
	v_pk_mul_f32 v[68:69], v[126:127], v[58:59] op_sel_hi:[1,0]
	v_pk_mul_f32 v[44:45], v[236:237], v[62:63]
	v_pk_mul_f32 v[42:43], v[234:235], v[64:65]
	v_pk_mul_f32 v[48:49], v[240:241], v[66:67]
	v_pk_mul_f32 v[46:47], v[238:239], v[68:69]
	v_cvt_pk_bf16_f32 v42, v42, v43
	v_cvt_pk_bf16_f32 v43, v44, v45
	v_cvt_pk_bf16_f32 v44, v46, v47
	v_cvt_pk_bf16_f32 v45, v48, v49
	global_store_dwordx4 v[60:61], v[42:45], off
	s_nop 0
	v_pk_mul_f32 v[62:63], v[120:121], v[58:59] op_sel_hi:[1,0]
	v_pk_mul_f32 v[64:65], v[118:119], v[58:59] op_sel_hi:[1,0]
	v_pk_mul_f32 v[66:67], v[116:117], v[58:59] op_sel_hi:[1,0]
	v_pk_mul_f32 v[58:59], v[114:115], v[58:59] op_sel_hi:[1,0]
	v_pk_mul_f32 v[44:45], v[62:63], v[244:245]
	v_pk_mul_f32 v[42:43], v[64:65], v[242:243]
	v_pk_mul_f32 v[48:49], v[66:67], v[248:249]
	v_pk_mul_f32 v[46:47], v[58:59], v[246:247]
	v_cvt_pk_bf16_f32 v42, v42, v43
	v_cvt_pk_bf16_f32 v43, v44, v45
	v_cvt_pk_bf16_f32 v44, v46, v47
	v_cvt_pk_bf16_f32 v45, v48, v49
	global_store_dwordx4 v[60:61], v[42:45], off offset:256
	ds_read_b32 v58, v185
	v_lshlrev_b64 v[60:61], 11, v[152:153]
	v_lshl_add_u64 v[60:61], s[4:5], 0, v[60:61]
	v_lshl_add_u64 v[60:61], v[60:61], 0, v[142:143]
	s_waitcnt lgkmcnt(0)
; __device__ __forceinline__ unsigned cvt_pk_bf16(float lo, float hi) { const f32x2 v = {lo, hi}; const bf16x2_t b = __builtin_convertvector(v, bf16x2_t); return __builtin_bit_cast(unsigned, b); }
;     __device__ __forceinline__ void operator()(f32x4 (&acc)[2][2][4][2], const Unit& u, int wr, int wc, int fr, int fq) const {
;     ...
;                 for (int m = 0; m < 4; ++m) { const int rl = ai * 128 + wr * 64 + m * 16 + fr; const float r2 = S[rl]; const size_t off = (size_t)(u.pm * 256 + rl) * DM + col0;
; #pragma unroll
;                     for (int bj = 0; bj < 2; ++bj) { const f32x4 ga = *(const f32x4*)(gnext + col0 + bj * 128), gb = *(const f32x4*)(gnext + col0 + bj * 128 + 4);
;                         const f32x4 v0 = acc[ai][bj][m][0] * r2 * ga, v1 = acc[ai][bj][m][1] * r2 * gb;
;                         u32x4 w; w.x = cvt_pk_bf16(v0[0], v0[1]); w.y = cvt_pk_bf16(v0[2], v0[3]); w.z = cvt_pk_bf16(v1[0], v1[1]); w.w = cvt_pk_bf16(v1[2], v1[3]);
;                         *(u32x4*)(XN + off + bj * 128) = w; }
;                     asm volatile("" ::: "memory"); }
	v_pk_mul_f32 v[62:63], v[96:97], v[58:59] op_sel_hi:[1,0]
	v_pk_mul_f32 v[64:65], v[94:95], v[58:59] op_sel_hi:[1,0]
	v_pk_mul_f32 v[66:67], v[92:93], v[58:59] op_sel_hi:[1,0]
	v_pk_mul_f32 v[68:69], v[90:91], v[58:59] op_sel_hi:[1,0]
	v_pk_mul_f32 v[44:45], v[236:237], v[62:63]
	v_pk_mul_f32 v[42:43], v[234:235], v[64:65]
	v_pk_mul_f32 v[48:49], v[240:241], v[66:67]
	v_pk_mul_f32 v[46:47], v[238:239], v[68:69]
	v_cvt_pk_bf16_f32 v42, v42, v43
	v_cvt_pk_bf16_f32 v43, v44, v45
	v_cvt_pk_bf16_f32 v44, v46, v47
	v_cvt_pk_bf16_f32 v45, v48, v49
	global_store_dwordx4 v[60:61], v[42:45], off
	s_nop 0
	v_pk_mul_f32 v[62:63], v[80:81], v[58:59] op_sel_hi:[1,0]
	v_pk_mul_f32 v[64:65], v[78:79], v[58:59] op_sel_hi:[1,0]
	v_pk_mul_f32 v[66:67], v[76:77], v[58:59] op_sel_hi:[1,0]
	v_pk_mul_f32 v[58:59], v[74:75], v[58:59] op_sel_hi:[1,0]
	v_pk_mul_f32 v[44:45], v[62:63], v[244:245]
	v_pk_mul_f32 v[42:43], v[64:65], v[242:243]
	v_pk_mul_f32 v[48:49], v[66:67], v[248:249]
	v_pk_mul_f32 v[46:47], v[58:59], v[246:247]
	v_cvt_pk_bf16_f32 v42, v42, v43
	v_cvt_pk_bf16_f32 v43, v44, v45
	v_cvt_pk_bf16_f32 v44, v46, v47
	v_cvt_pk_bf16_f32 v45, v48, v49
	global_store_dwordx4 v[60:61], v[42:45], off offset:256
	ds_read_b32 v58, v186
	v_lshlrev_b64 v[60:61], 11, v[156:157]
	v_lshl_add_u64 v[60:61], s[4:5], 0, v[60:61]
	v_lshl_add_u64 v[60:61], v[60:61], 0, v[142:143]
	s_waitcnt lgkmcnt(0)
	v_pk_mul_f32 v[56:57], v[56:57], v[58:59] op_sel_hi:[1,0]
	v_pk_mul_f32 v[54:55], v[54:55], v[58:59] op_sel_hi:[1,0]
	v_pk_mul_f32 v[52:53], v[52:53], v[58:59] op_sel_hi:[1,0]
	v_pk_mul_f32 v[50:51], v[50:51], v[58:59] op_sel_hi:[1,0]
	v_pk_mul_f32 v[40:41], v[40:41], v[58:59] op_sel_hi:[1,0]
	v_pk_mul_f32 v[38:39], v[38:39], v[58:59] op_sel_hi:[1,0]
	v_pk_mul_f32 v[36:37], v[36:37], v[58:59] op_sel_hi:[1,0]
	v_pk_mul_f32 v[34:35], v[34:35], v[58:59] op_sel_hi:[1,0]
	v_pk_mul_f32 v[44:45], v[236:237], v[56:57]
	v_pk_mul_f32 v[42:43], v[234:235], v[54:55]
	v_pk_mul_f32 v[48:49], v[240:241], v[52:53]
	v_pk_mul_f32 v[46:47], v[238:239], v[50:51]
	v_cvt_pk_bf16_f32 v42, v42, v43
	v_cvt_pk_bf16_f32 v43, v44, v45
	v_cvt_pk_bf16_f32 v44, v46, v47
	v_cvt_pk_bf16_f32 v45, v48, v49
	global_store_dwordx4 v[60:61], v[42:45], off
	s_nop 0
	v_pk_mul_f32 v[40:41], v[40:41], v[244:245]
	v_pk_mul_f32 v[38:39], v[38:39], v[242:243]
	v_pk_mul_f32 v[42:43], v[36:37], v[248:249]
	v_pk_mul_f32 v[36:37], v[34:35], v[246:247]
	v_cvt_pk_bf16_f32 v34, v38, v39
	v_cvt_pk_bf16_f32 v35, v40, v41
	v_cvt_pk_bf16_f32 v36, v36, v37
	v_cvt_pk_bf16_f32 v37, v42, v43
	global_store_dwordx4 v[60:61], v[34:37], off offset:256
	ds_read_b32 v42, v187
	v_lshlrev_b64 v[44:45], 11, v[158:159]
	v_lshl_add_u64 v[44:45], s[4:5], 0, v[44:45]
	v_lshl_add_u64 v[44:45], v[44:45], 0, v[142:143]
	s_waitcnt lgkmcnt(0)
	v_pk_mul_f32 v[32:33], v[32:33], v[42:43] op_sel_hi:[1,0]
	v_pk_mul_f32 v[30:31], v[30:31], v[42:43] op_sel_hi:[1,0]
	v_pk_mul_f32 v[28:29], v[28:29], v[42:43] op_sel_hi:[1,0]
	v_pk_mul_f32 v[26:27], v[26:27], v[42:43] op_sel_hi:[1,0]
	v_pk_mul_f32 v[24:25], v[24:25], v[42:43] op_sel_hi:[1,0]
	v_pk_mul_f32 v[22:23], v[22:23], v[42:43] op_sel_hi:[1,0]
	v_pk_mul_f32 v[20:21], v[20:21], v[42:43] op_sel_hi:[1,0]
	v_pk_mul_f32 v[18:19], v[18:19], v[42:43] op_sel_hi:[1,0]
	v_pk_mul_f32 v[32:33], v[236:237], v[32:33]
	v_pk_mul_f32 v[30:31], v[234:235], v[30:31]
	v_pk_mul_f32 v[34:35], v[240:241], v[28:29]
	v_pk_mul_f32 v[28:29], v[238:239], v[26:27]
	v_cvt_pk_bf16_f32 v26, v30, v31
	v_cvt_pk_bf16_f32 v27, v32, v33
	v_cvt_pk_bf16_f32 v28, v28, v29
	v_cvt_pk_bf16_f32 v29, v34, v35
	global_store_dwordx4 v[44:45], v[26:29], off
	s_nop 0
	v_pk_mul_f32 v[24:25], v[24:25], v[244:245]
	v_pk_mul_f32 v[22:23], v[22:23], v[242:243]
	v_pk_mul_f32 v[26:27], v[20:21], v[248:249]
	v_pk_mul_f32 v[20:21], v[18:19], v[246:247]
	v_cvt_pk_bf16_f32 v18, v22, v23
	v_cvt_pk_bf16_f32 v19, v24, v25
	v_cvt_pk_bf16_f32 v20, v20, v21
	v_cvt_pk_bf16_f32 v21, v26, v27
	global_store_dwordx4 v[44:45], v[18:21], off offset:256
	ds_read_b32 v26, v188
	v_lshlrev_b64 v[28:29], 11, v[166:167]
	v_lshl_add_u64 v[28:29], s[4:5], 0, v[28:29]
	v_lshl_add_u64 v[28:29], v[28:29], 0, v[142:143]
	s_waitcnt lgkmcnt(0)
	v_pk_mul_f32 v[16:17], v[16:17], v[26:27] op_sel_hi:[1,0]
	v_pk_mul_f32 v[14:15], v[14:15], v[26:27] op_sel_hi:[1,0]
	v_pk_mul_f32 v[12:13], v[12:13], v[26:27] op_sel_hi:[1,0]
	v_pk_mul_f32 v[10:11], v[10:11], v[26:27] op_sel_hi:[1,0]
	v_pk_mul_f32 v[8:9], v[8:9], v[26:27] op_sel_hi:[1,0]
	v_pk_mul_f32 v[6:7], v[6:7], v[26:27] op_sel_hi:[1,0]
	v_pk_mul_f32 v[4:5], v[4:5], v[26:27] op_sel_hi:[1,0]
	v_pk_mul_f32 v[2:3], v[2:3], v[26:27] op_sel_hi:[1,0]
	v_pk_mul_f32 v[16:17], v[236:237], v[16:17]
	v_pk_mul_f32 v[14:15], v[234:235], v[14:15]
	v_pk_mul_f32 v[18:19], v[240:241], v[12:13]
	v_pk_mul_f32 v[12:13], v[238:239], v[10:11]
	v_cvt_pk_bf16_f32 v10, v14, v15
	v_cvt_pk_bf16_f32 v11, v16, v17
	v_cvt_pk_bf16_f32 v12, v12, v13
	v_cvt_pk_bf16_f32 v13, v18, v19
	global_store_dwordx4 v[28:29], v[10:13], off
	s_nop 0
	v_pk_mul_f32 v[8:9], v[8:9], v[244:245]
	v_pk_mul_f32 v[6:7], v[6:7], v[242:243]
	v_pk_mul_f32 v[10:11], v[4:5], v[248:249]
	v_pk_mul_f32 v[4:5], v[2:3], v[246:247]
	v_cvt_pk_bf16_f32 v2, v6, v7
	v_cvt_pk_bf16_f32 v3, v8, v9
	v_cvt_pk_bf16_f32 v4, v4, v5
	v_cvt_pk_bf16_f32 v5, v10, v11
	global_store_dwordx4 v[28:29], v[2:5], off offset:256
